# P10 final post-LN rows hand-written (same generator as P5, single LN, f32 out)
# speedup vs baseline: 1.0071x; 1.0070x over previous
.LBB0_1448:
	s_or_b64 exec, exec, s[2:3]
	s_waitcnt lgkmcnt(0)
	s_barrier
	s_mov_b32 s5, 0x8000
	v_ashrrev_i32_e32 v0, 6, v208
	v_add_u32_e32 v38, s60, v0
	v_cmp_gt_i32_e32 vcc, s5, v38
	s_and_saveexec_b64 s[2:3], vcc
	s_add_u32 s46, s90, 0xec00000
	s_addc_u32 s47, s91, 0
	s_add_u32 s48, s64, 0x1000
	s_addc_u32 s49, s65, 0
	s_add_u32 s50, s66, 0x1000
	s_addc_u32 s51, s67, 0
	v_lshrrev_b32_e32 v168, 6, v208
	v_and_b32_e32 v169, 63, v208
	v_readfirstlane_b32 s42, v168
	v_lshlrev_b32_e32 v176, 4, v169
	v_lshlrev_b32_e32 v177, 3, v169
	s_nop 1
	s_add_u32 s1, s60, s42
	s_lshl_b32 s42, s1, 16
	s_add_u32 s14, s46, s42
	s_addc_u32 s15, s47, 0
	s_add_u32 s8, s88, s42
	s_addc_u32 s9, s89, 0
	s_lshr_b32 s42, s42, 1
	s_add_u32 s6, s90, s42
	s_addc_u32 s7, s91, 0
	s_add_u32 s12, s6, 0x2400000
	s_addc_u32 s13, s7, 0
	s_add_u32 s6, s6, 0x16c00000
	s_addc_u32 s7, s7, 0
	s_lshr_b32 s42, s1, 7
	s_mul_i32 s42, s42, 0x3000
	s_add_u32 s38, s90, s42
	s_addc_u32 s39, s91, 0
	s_add_u32 s38, s38, 0x21b3000
	s_addc_u32 s39, s39, 0
	s_add_u32 s40, s38, 0x1000
	s_addc_u32 s41, s39, 0
	global_load_dwordx4 v[0:3], v176, s[48:49] offset:0
	global_load_dwordx4 v[4:7], v176, s[48:49] offset:1024
	global_load_dwordx4 v[8:11], v176, s[48:49] offset:2048
	global_load_dwordx4 v[12:15], v176, s[48:49] offset:3072
	global_load_dwordx4 v[16:19], v176, s[50:51] offset:0
	global_load_dwordx4 v[20:23], v176, s[50:51] offset:1024
	global_load_dwordx4 v[24:27], v176, s[50:51] offset:2048
	global_load_dwordx4 v[28:31], v176, s[50:51] offset:3072
	global_load_dwordx4 v[32:35], v176, s[40:41] offset:0
	global_load_dwordx4 v[36:39], v176, s[40:41] offset:1024
	global_load_dwordx4 v[40:43], v176, s[40:41] offset:2048
	global_load_dwordx4 v[44:47], v176, s[40:41] offset:3072
	global_load_dwordx4 v[48:51], v176, s[38:39] offset:0
	global_load_dwordx4 v[52:55], v176, s[38:39] offset:1024
	global_load_dwordx4 v[56:59], v176, s[38:39] offset:2048
	global_load_dwordx4 v[60:63], v176, s[38:39] offset:3072
	v_mov_b32_e32 v172, 0xba800000
	v_mov_b32_e32 v173, 0xba800000
	v_mov_b32_e32 v178, 0x3a800000
	v_mov_b32_e32 v179, 0x358637bd
	s_mov_b32 s44, 0x3fb504f3
	s_mov_b32 s45, 0x3fb504f3
	global_load_dwordx4 v[64:67], v176, s[14:15] offset:0
	global_load_dwordx4 v[68:71], v176, s[14:15] offset:1024
	global_load_dwordx4 v[72:75], v176, s[14:15] offset:2048
	global_load_dwordx4 v[76:79], v176, s[14:15] offset:3072
	global_load_dwordx2 v[112:113], v177, s[6:7] offset:0
	global_load_dwordx2 v[114:115], v177, s[6:7] offset:512
	global_load_dwordx2 v[116:117], v177, s[6:7] offset:1024
	global_load_dwordx2 v[118:119], v177, s[6:7] offset:1536
	s_add_u32 s14, s14, 0x1000
	s_addc_u32 s15, s15, 0
	s_add_u32 s6, s6, 0x800
	s_addc_u32 s7, s7, 0
	global_load_dwordx4 v[80:83], v176, s[14:15] offset:0
	global_load_dwordx4 v[84:87], v176, s[14:15] offset:1024
	global_load_dwordx4 v[88:91], v176, s[14:15] offset:2048
	global_load_dwordx4 v[92:95], v176, s[14:15] offset:3072
	global_load_dwordx2 v[120:121], v177, s[6:7] offset:0
	global_load_dwordx2 v[122:123], v177, s[6:7] offset:512
	global_load_dwordx2 v[124:125], v177, s[6:7] offset:1024
	global_load_dwordx2 v[126:127], v177, s[6:7] offset:1536
	s_add_u32 s14, s14, 0x1000
	s_addc_u32 s15, s15, 0
	s_add_u32 s6, s6, 0x800
	s_addc_u32 s7, s7, 0
	global_load_dwordx4 v[96:99], v176, s[14:15] offset:0
	global_load_dwordx4 v[100:103], v176, s[14:15] offset:1024
	global_load_dwordx4 v[104:107], v176, s[14:15] offset:2048
	global_load_dwordx4 v[108:111], v176, s[14:15] offset:3072
	global_load_dwordx2 v[128:129], v177, s[6:7] offset:0
	global_load_dwordx2 v[130:131], v177, s[6:7] offset:512
	global_load_dwordx2 v[132:133], v177, s[6:7] offset:1024
	global_load_dwordx2 v[134:135], v177, s[6:7] offset:1536
	s_add_u32 s14, s14, 0x1000
	s_addc_u32 s15, s15, 0
	s_add_u32 s6, s6, 0x800
	s_addc_u32 s7, s7, 0
	s_waitcnt vmcnt(16)
	v_pk_add_f32 v[32:33], v[32:33], 1.0 op_sel_hi:[1,0]
	v_pk_add_f32 v[34:35], v[34:35], 1.0 op_sel_hi:[1,0]
	v_pk_add_f32 v[36:37], v[36:37], 1.0 op_sel_hi:[1,0]
	v_pk_add_f32 v[38:39], v[38:39], 1.0 op_sel_hi:[1,0]
	v_pk_add_f32 v[40:41], v[40:41], 1.0 op_sel_hi:[1,0]
	v_pk_add_f32 v[42:43], v[42:43], 1.0 op_sel_hi:[1,0]
	v_pk_add_f32 v[44:45], v[44:45], 1.0 op_sel_hi:[1,0]
	v_pk_add_f32 v[46:47], v[46:47], 1.0 op_sel_hi:[1,0]
	v_lshlrev_b32_e32 v136, 16, v112
	v_and_b32_e32 v137, 0xffff0000, v112
	v_lshlrev_b32_e32 v138, 16, v113
	v_and_b32_e32 v139, 0xffff0000, v113
	v_lshlrev_b32_e32 v140, 16, v114
	v_and_b32_e32 v141, 0xffff0000, v114
	v_lshlrev_b32_e32 v142, 16, v115
	v_and_b32_e32 v143, 0xffff0000, v115
	v_lshlrev_b32_e32 v144, 16, v116
	v_and_b32_e32 v145, 0xffff0000, v116
	v_lshlrev_b32_e32 v146, 16, v117
	v_and_b32_e32 v147, 0xffff0000, v117
	v_lshlrev_b32_e32 v148, 16, v118
	v_and_b32_e32 v149, 0xffff0000, v118
	v_lshlrev_b32_e32 v150, 16, v119
	v_and_b32_e32 v151, 0xffff0000, v119
	v_pk_fma_f32 v[136:137], v[64:65], s[44:45], v[136:137]
	v_pk_fma_f32 v[138:139], v[66:67], s[44:45], v[138:139]
	v_pk_fma_f32 v[140:141], v[68:69], s[44:45], v[140:141]
	v_pk_fma_f32 v[142:143], v[70:71], s[44:45], v[142:143]
	v_pk_fma_f32 v[144:145], v[72:73], s[44:45], v[144:145]
	v_pk_fma_f32 v[146:147], v[74:75], s[44:45], v[146:147]
	v_pk_fma_f32 v[148:149], v[76:77], s[44:45], v[148:149]
	v_pk_fma_f32 v[150:151], v[78:79], s[44:45], v[150:151]
	v_pk_add_f32 v[152:153], v[136:137], v[138:139]
	v_pk_add_f32 v[152:153], v[152:153], v[140:141]
	v_pk_add_f32 v[152:153], v[152:153], v[142:143]
	v_pk_add_f32 v[152:153], v[152:153], v[144:145]
	v_pk_add_f32 v[152:153], v[152:153], v[146:147]
	v_pk_add_f32 v[152:153], v[152:153], v[148:149]
	v_pk_add_f32 v[152:153], v[152:153], v[150:151]
	v_add_f32_e32 v170, v152, v153
	s_nop 1
	v_add_f32_dpp v168, v170, v170 quad_perm:[1,0,3,2] row_mask:0xf bank_mask:0xf
	s_nop 1
	v_add_f32_dpp v168, v168, v168 quad_perm:[2,3,0,1] row_mask:0xf bank_mask:0xf
	s_nop 1
	v_add_f32_dpp v168, v168, v168 row_half_mirror row_mask:0xf bank_mask:0xf
	s_nop 1
	v_add_f32_dpp v168, v168, v168 row_mirror row_mask:0xf bank_mask:0xf
	s_nop 1
	v_add_f32_dpp v168, v168, v168 row_bcast:15 row_mask:0xa bank_mask:0xf
	s_nop 1
	v_add_f32_dpp v168, v168, v168 row_bcast:31 row_mask:0xc bank_mask:0xf
	s_nop 1
	v_readlane_b32 s42, v168, 63
	s_nop 3
	s_mov_b32 s43, s42
	v_pk_fma_f32 v[136:137], s[42:43], v[172:173], v[136:137]
	v_pk_fma_f32 v[138:139], s[42:43], v[172:173], v[138:139]
	v_pk_fma_f32 v[140:141], s[42:43], v[172:173], v[140:141]
	v_pk_fma_f32 v[142:143], s[42:43], v[172:173], v[142:143]
	v_pk_fma_f32 v[144:145], s[42:43], v[172:173], v[144:145]
	v_pk_fma_f32 v[146:147], s[42:43], v[172:173], v[146:147]
	v_pk_fma_f32 v[148:149], s[42:43], v[172:173], v[148:149]
	v_pk_fma_f32 v[150:151], s[42:43], v[172:173], v[150:151]
	v_pk_mul_f32 v[152:153], v[136:137], v[136:137]
	v_pk_fma_f32 v[152:153], v[138:139], v[138:139], v[152:153]
	v_pk_fma_f32 v[152:153], v[140:141], v[140:141], v[152:153]
	v_pk_fma_f32 v[152:153], v[142:143], v[142:143], v[152:153]
	v_pk_fma_f32 v[152:153], v[144:145], v[144:145], v[152:153]
	v_pk_fma_f32 v[152:153], v[146:147], v[146:147], v[152:153]
	v_pk_fma_f32 v[152:153], v[148:149], v[148:149], v[152:153]
	v_pk_fma_f32 v[152:153], v[150:151], v[150:151], v[152:153]
	v_add_f32_e32 v170, v152, v153
	s_nop 1
	v_add_f32_dpp v168, v170, v170 quad_perm:[1,0,3,2] row_mask:0xf bank_mask:0xf
	s_nop 1
	v_add_f32_dpp v168, v168, v168 quad_perm:[2,3,0,1] row_mask:0xf bank_mask:0xf
	s_nop 1
	v_add_f32_dpp v168, v168, v168 row_half_mirror row_mask:0xf bank_mask:0xf
	s_nop 1
	v_add_f32_dpp v168, v168, v168 row_mirror row_mask:0xf bank_mask:0xf
	s_nop 1
	v_add_f32_dpp v168, v168, v168 row_bcast:15 row_mask:0xa bank_mask:0xf
	s_nop 1
	v_add_f32_dpp v168, v168, v168 row_bcast:31 row_mask:0xc bank_mask:0xf
	s_nop 1
	v_readlane_b32 s42, v168, 63
	s_nop 3
	v_fma_f32 v174, s42, v178, v179
	v_rsq_f32_e32 v174, v174
	s_nop 0
	v_pk_mul_f32 v[136:137], v[136:137], v[174:175] op_sel_hi:[1,0]
	v_pk_mul_f32 v[138:139], v[138:139], v[174:175] op_sel_hi:[1,0]
	v_pk_mul_f32 v[140:141], v[140:141], v[174:175] op_sel_hi:[1,0]
	v_pk_mul_f32 v[142:143], v[142:143], v[174:175] op_sel_hi:[1,0]
	v_pk_mul_f32 v[144:145], v[144:145], v[174:175] op_sel_hi:[1,0]
	v_pk_mul_f32 v[146:147], v[146:147], v[174:175] op_sel_hi:[1,0]
	v_pk_mul_f32 v[148:149], v[148:149], v[174:175] op_sel_hi:[1,0]
	v_pk_mul_f32 v[150:151], v[150:151], v[174:175] op_sel_hi:[1,0]
	v_pk_fma_f32 v[136:137], v[136:137], v[0:1], v[16:17]
	v_pk_fma_f32 v[138:139], v[138:139], v[2:3], v[18:19]
	v_pk_fma_f32 v[140:141], v[140:141], v[4:5], v[20:21]
	v_pk_fma_f32 v[142:143], v[142:143], v[6:7], v[22:23]
	v_pk_fma_f32 v[144:145], v[144:145], v[8:9], v[24:25]
	v_pk_fma_f32 v[146:147], v[146:147], v[10:11], v[26:27]
	v_pk_fma_f32 v[148:149], v[148:149], v[12:13], v[28:29]
	v_pk_fma_f32 v[150:151], v[150:151], v[14:15], v[30:31]
	global_store_dwordx4 v176, v[136:139], s[8:9] offset:0
	global_store_dwordx4 v176, v[140:143], s[8:9] offset:1024
	global_store_dwordx4 v176, v[144:147], s[8:9] offset:2048
	global_store_dwordx4 v176, v[148:151], s[8:9] offset:3072
	s_add_u32 s8, s8, 0x1000
	s_addc_u32 s9, s9, 0
	s_add_u32 s12, s12, 0x800
	s_addc_u32 s13, s13, 0
	global_load_dwordx4 v[64:67], v176, s[14:15] offset:0
	global_load_dwordx4 v[68:71], v176, s[14:15] offset:1024
	global_load_dwordx4 v[72:75], v176, s[14:15] offset:2048
	global_load_dwordx4 v[76:79], v176, s[14:15] offset:3072
	global_load_dwordx2 v[112:113], v177, s[6:7] offset:0
	global_load_dwordx2 v[114:115], v177, s[6:7] offset:512
	global_load_dwordx2 v[116:117], v177, s[6:7] offset:1024
	global_load_dwordx2 v[118:119], v177, s[6:7] offset:1536
	s_add_u32 s14, s14, 0x1000
	s_addc_u32 s15, s15, 0
	s_add_u32 s6, s6, 0x800
	s_addc_u32 s7, s7, 0
	s_waitcnt vmcnt(20)
	v_lshlrev_b32_e32 v136, 16, v120
	v_and_b32_e32 v137, 0xffff0000, v120
	v_lshlrev_b32_e32 v138, 16, v121
	v_and_b32_e32 v139, 0xffff0000, v121
	v_lshlrev_b32_e32 v140, 16, v122
	v_and_b32_e32 v141, 0xffff0000, v122
	v_lshlrev_b32_e32 v142, 16, v123
	v_and_b32_e32 v143, 0xffff0000, v123
	v_lshlrev_b32_e32 v144, 16, v124
	v_and_b32_e32 v145, 0xffff0000, v124
	v_lshlrev_b32_e32 v146, 16, v125
	v_and_b32_e32 v147, 0xffff0000, v125
	v_lshlrev_b32_e32 v148, 16, v126
	v_and_b32_e32 v149, 0xffff0000, v126
	v_lshlrev_b32_e32 v150, 16, v127
	v_and_b32_e32 v151, 0xffff0000, v127
	v_pk_fma_f32 v[136:137], v[80:81], s[44:45], v[136:137]
	v_pk_fma_f32 v[138:139], v[82:83], s[44:45], v[138:139]
	v_pk_fma_f32 v[140:141], v[84:85], s[44:45], v[140:141]
	v_pk_fma_f32 v[142:143], v[86:87], s[44:45], v[142:143]
	v_pk_fma_f32 v[144:145], v[88:89], s[44:45], v[144:145]
	v_pk_fma_f32 v[146:147], v[90:91], s[44:45], v[146:147]
	v_pk_fma_f32 v[148:149], v[92:93], s[44:45], v[148:149]
	v_pk_fma_f32 v[150:151], v[94:95], s[44:45], v[150:151]
	v_pk_add_f32 v[152:153], v[136:137], v[138:139]
	v_pk_add_f32 v[152:153], v[152:153], v[140:141]
	v_pk_add_f32 v[152:153], v[152:153], v[142:143]
	v_pk_add_f32 v[152:153], v[152:153], v[144:145]
	v_pk_add_f32 v[152:153], v[152:153], v[146:147]
	v_pk_add_f32 v[152:153], v[152:153], v[148:149]
	v_pk_add_f32 v[152:153], v[152:153], v[150:151]
	v_add_f32_e32 v170, v152, v153
	s_nop 1
	v_add_f32_dpp v168, v170, v170 quad_perm:[1,0,3,2] row_mask:0xf bank_mask:0xf
	s_nop 1
	v_add_f32_dpp v168, v168, v168 quad_perm:[2,3,0,1] row_mask:0xf bank_mask:0xf
	s_nop 1
	v_add_f32_dpp v168, v168, v168 row_half_mirror row_mask:0xf bank_mask:0xf
	s_nop 1
	v_add_f32_dpp v168, v168, v168 row_mirror row_mask:0xf bank_mask:0xf
	s_nop 1
	v_add_f32_dpp v168, v168, v168 row_bcast:15 row_mask:0xa bank_mask:0xf
	s_nop 1
	v_add_f32_dpp v168, v168, v168 row_bcast:31 row_mask:0xc bank_mask:0xf
	s_nop 1
	v_readlane_b32 s42, v168, 63
	s_nop 3
	s_mov_b32 s43, s42
	v_pk_fma_f32 v[136:137], s[42:43], v[172:173], v[136:137]
	v_pk_fma_f32 v[138:139], s[42:43], v[172:173], v[138:139]
	v_pk_fma_f32 v[140:141], s[42:43], v[172:173], v[140:141]
	v_pk_fma_f32 v[142:143], s[42:43], v[172:173], v[142:143]
	v_pk_fma_f32 v[144:145], s[42:43], v[172:173], v[144:145]
	v_pk_fma_f32 v[146:147], s[42:43], v[172:173], v[146:147]
	v_pk_fma_f32 v[148:149], s[42:43], v[172:173], v[148:149]
	v_pk_fma_f32 v[150:151], s[42:43], v[172:173], v[150:151]
	v_pk_mul_f32 v[152:153], v[136:137], v[136:137]
	v_pk_fma_f32 v[152:153], v[138:139], v[138:139], v[152:153]
	v_pk_fma_f32 v[152:153], v[140:141], v[140:141], v[152:153]
	v_pk_fma_f32 v[152:153], v[142:143], v[142:143], v[152:153]
	v_pk_fma_f32 v[152:153], v[144:145], v[144:145], v[152:153]
	v_pk_fma_f32 v[152:153], v[146:147], v[146:147], v[152:153]
	v_pk_fma_f32 v[152:153], v[148:149], v[148:149], v[152:153]
	v_pk_fma_f32 v[152:153], v[150:151], v[150:151], v[152:153]
	v_add_f32_e32 v170, v152, v153
	s_nop 1
	v_add_f32_dpp v168, v170, v170 quad_perm:[1,0,3,2] row_mask:0xf bank_mask:0xf
	s_nop 1
	v_add_f32_dpp v168, v168, v168 quad_perm:[2,3,0,1] row_mask:0xf bank_mask:0xf
	s_nop 1
	v_add_f32_dpp v168, v168, v168 row_half_mirror row_mask:0xf bank_mask:0xf
	s_nop 1
	v_add_f32_dpp v168, v168, v168 row_mirror row_mask:0xf bank_mask:0xf
	s_nop 1
	v_add_f32_dpp v168, v168, v168 row_bcast:15 row_mask:0xa bank_mask:0xf
	s_nop 1
	v_add_f32_dpp v168, v168, v168 row_bcast:31 row_mask:0xc bank_mask:0xf
	s_nop 1
	v_readlane_b32 s42, v168, 63
	s_nop 3
	v_fma_f32 v174, s42, v178, v179
	v_rsq_f32_e32 v174, v174
	s_nop 0
	v_pk_mul_f32 v[136:137], v[136:137], v[174:175] op_sel_hi:[1,0]
	v_pk_mul_f32 v[138:139], v[138:139], v[174:175] op_sel_hi:[1,0]
	v_pk_mul_f32 v[140:141], v[140:141], v[174:175] op_sel_hi:[1,0]
	v_pk_mul_f32 v[142:143], v[142:143], v[174:175] op_sel_hi:[1,0]
	v_pk_mul_f32 v[144:145], v[144:145], v[174:175] op_sel_hi:[1,0]
	v_pk_mul_f32 v[146:147], v[146:147], v[174:175] op_sel_hi:[1,0]
	v_pk_mul_f32 v[148:149], v[148:149], v[174:175] op_sel_hi:[1,0]
	v_pk_mul_f32 v[150:151], v[150:151], v[174:175] op_sel_hi:[1,0]
	v_pk_fma_f32 v[136:137], v[136:137], v[0:1], v[16:17]
	v_pk_fma_f32 v[138:139], v[138:139], v[2:3], v[18:19]
	v_pk_fma_f32 v[140:141], v[140:141], v[4:5], v[20:21]
	v_pk_fma_f32 v[142:143], v[142:143], v[6:7], v[22:23]
	v_pk_fma_f32 v[144:145], v[144:145], v[8:9], v[24:25]
	v_pk_fma_f32 v[146:147], v[146:147], v[10:11], v[26:27]
	v_pk_fma_f32 v[148:149], v[148:149], v[12:13], v[28:29]
	v_pk_fma_f32 v[150:151], v[150:151], v[14:15], v[30:31]
	global_store_dwordx4 v176, v[136:139], s[8:9] offset:0
	global_store_dwordx4 v176, v[140:143], s[8:9] offset:1024
	global_store_dwordx4 v176, v[144:147], s[8:9] offset:2048
	global_store_dwordx4 v176, v[148:151], s[8:9] offset:3072
	s_add_u32 s8, s8, 0x1000
	s_addc_u32 s9, s9, 0
	s_add_u32 s12, s12, 0x800
	s_addc_u32 s13, s13, 0
	global_load_dwordx4 v[80:83], v176, s[14:15] offset:0
	global_load_dwordx4 v[84:87], v176, s[14:15] offset:1024
	global_load_dwordx4 v[88:91], v176, s[14:15] offset:2048
	global_load_dwordx4 v[92:95], v176, s[14:15] offset:3072
	global_load_dwordx2 v[120:121], v177, s[6:7] offset:0
	global_load_dwordx2 v[122:123], v177, s[6:7] offset:512
	global_load_dwordx2 v[124:125], v177, s[6:7] offset:1024
	global_load_dwordx2 v[126:127], v177, s[6:7] offset:1536
	s_add_u32 s14, s14, 0x1000
	s_addc_u32 s15, s15, 0
	s_add_u32 s6, s6, 0x800
	s_addc_u32 s7, s7, 0
	s_waitcnt vmcnt(24)
	v_lshlrev_b32_e32 v136, 16, v128
	v_and_b32_e32 v137, 0xffff0000, v128
	v_lshlrev_b32_e32 v138, 16, v129
	v_and_b32_e32 v139, 0xffff0000, v129
	v_lshlrev_b32_e32 v140, 16, v130
	v_and_b32_e32 v141, 0xffff0000, v130
	v_lshlrev_b32_e32 v142, 16, v131
	v_and_b32_e32 v143, 0xffff0000, v131
	v_lshlrev_b32_e32 v144, 16, v132
	v_and_b32_e32 v145, 0xffff0000, v132
	v_lshlrev_b32_e32 v146, 16, v133
	v_and_b32_e32 v147, 0xffff0000, v133
	v_lshlrev_b32_e32 v148, 16, v134
	v_and_b32_e32 v149, 0xffff0000, v134
	v_lshlrev_b32_e32 v150, 16, v135
	v_and_b32_e32 v151, 0xffff0000, v135
	v_pk_fma_f32 v[136:137], v[96:97], s[44:45], v[136:137]
	v_pk_fma_f32 v[138:139], v[98:99], s[44:45], v[138:139]
	v_pk_fma_f32 v[140:141], v[100:101], s[44:45], v[140:141]
	v_pk_fma_f32 v[142:143], v[102:103], s[44:45], v[142:143]
	v_pk_fma_f32 v[144:145], v[104:105], s[44:45], v[144:145]
	v_pk_fma_f32 v[146:147], v[106:107], s[44:45], v[146:147]
	v_pk_fma_f32 v[148:149], v[108:109], s[44:45], v[148:149]
	v_pk_fma_f32 v[150:151], v[110:111], s[44:45], v[150:151]
	v_pk_add_f32 v[152:153], v[136:137], v[138:139]
	v_pk_add_f32 v[152:153], v[152:153], v[140:141]
	v_pk_add_f32 v[152:153], v[152:153], v[142:143]
	v_pk_add_f32 v[152:153], v[152:153], v[144:145]
	v_pk_add_f32 v[152:153], v[152:153], v[146:147]
	v_pk_add_f32 v[152:153], v[152:153], v[148:149]
	v_pk_add_f32 v[152:153], v[152:153], v[150:151]
	v_add_f32_e32 v170, v152, v153
	s_nop 1
	v_add_f32_dpp v168, v170, v170 quad_perm:[1,0,3,2] row_mask:0xf bank_mask:0xf
	s_nop 1
	v_add_f32_dpp v168, v168, v168 quad_perm:[2,3,0,1] row_mask:0xf bank_mask:0xf
	s_nop 1
	v_add_f32_dpp v168, v168, v168 row_half_mirror row_mask:0xf bank_mask:0xf
	s_nop 1
	v_add_f32_dpp v168, v168, v168 row_mirror row_mask:0xf bank_mask:0xf
	s_nop 1
	v_add_f32_dpp v168, v168, v168 row_bcast:15 row_mask:0xa bank_mask:0xf
	s_nop 1
	v_add_f32_dpp v168, v168, v168 row_bcast:31 row_mask:0xc bank_mask:0xf
	s_nop 1
	v_readlane_b32 s42, v168, 63
	s_nop 3
	s_mov_b32 s43, s42
	v_pk_fma_f32 v[136:137], s[42:43], v[172:173], v[136:137]
	v_pk_fma_f32 v[138:139], s[42:43], v[172:173], v[138:139]
	v_pk_fma_f32 v[140:141], s[42:43], v[172:173], v[140:141]
	v_pk_fma_f32 v[142:143], s[42:43], v[172:173], v[142:143]
	v_pk_fma_f32 v[144:145], s[42:43], v[172:173], v[144:145]
	v_pk_fma_f32 v[146:147], s[42:43], v[172:173], v[146:147]
	v_pk_fma_f32 v[148:149], s[42:43], v[172:173], v[148:149]
	v_pk_fma_f32 v[150:151], s[42:43], v[172:173], v[150:151]
	v_pk_mul_f32 v[152:153], v[136:137], v[136:137]
	v_pk_fma_f32 v[152:153], v[138:139], v[138:139], v[152:153]
	v_pk_fma_f32 v[152:153], v[140:141], v[140:141], v[152:153]
	v_pk_fma_f32 v[152:153], v[142:143], v[142:143], v[152:153]
	v_pk_fma_f32 v[152:153], v[144:145], v[144:145], v[152:153]
	v_pk_fma_f32 v[152:153], v[146:147], v[146:147], v[152:153]
	v_pk_fma_f32 v[152:153], v[148:149], v[148:149], v[152:153]
	v_pk_fma_f32 v[152:153], v[150:151], v[150:151], v[152:153]
	v_add_f32_e32 v170, v152, v153
	s_nop 1
	v_add_f32_dpp v168, v170, v170 quad_perm:[1,0,3,2] row_mask:0xf bank_mask:0xf
	s_nop 1
	v_add_f32_dpp v168, v168, v168 quad_perm:[2,3,0,1] row_mask:0xf bank_mask:0xf
	s_nop 1
	v_add_f32_dpp v168, v168, v168 row_half_mirror row_mask:0xf bank_mask:0xf
	s_nop 1
	v_add_f32_dpp v168, v168, v168 row_mirror row_mask:0xf bank_mask:0xf
	s_nop 1
	v_add_f32_dpp v168, v168, v168 row_bcast:15 row_mask:0xa bank_mask:0xf
	s_nop 1
	v_add_f32_dpp v168, v168, v168 row_bcast:31 row_mask:0xc bank_mask:0xf
	s_nop 1
	v_readlane_b32 s42, v168, 63
	s_nop 3
	v_fma_f32 v174, s42, v178, v179
	v_rsq_f32_e32 v174, v174
	s_nop 0
	v_pk_mul_f32 v[136:137], v[136:137], v[174:175] op_sel_hi:[1,0]
	v_pk_mul_f32 v[138:139], v[138:139], v[174:175] op_sel_hi:[1,0]
	v_pk_mul_f32 v[140:141], v[140:141], v[174:175] op_sel_hi:[1,0]
	v_pk_mul_f32 v[142:143], v[142:143], v[174:175] op_sel_hi:[1,0]
	v_pk_mul_f32 v[144:145], v[144:145], v[174:175] op_sel_hi:[1,0]
	v_pk_mul_f32 v[146:147], v[146:147], v[174:175] op_sel_hi:[1,0]
	v_pk_mul_f32 v[148:149], v[148:149], v[174:175] op_sel_hi:[1,0]
	v_pk_mul_f32 v[150:151], v[150:151], v[174:175] op_sel_hi:[1,0]
	v_pk_fma_f32 v[136:137], v[136:137], v[0:1], v[16:17]
	v_pk_fma_f32 v[138:139], v[138:139], v[2:3], v[18:19]
	v_pk_fma_f32 v[140:141], v[140:141], v[4:5], v[20:21]
	v_pk_fma_f32 v[142:143], v[142:143], v[6:7], v[22:23]
	v_pk_fma_f32 v[144:145], v[144:145], v[8:9], v[24:25]
	v_pk_fma_f32 v[146:147], v[146:147], v[10:11], v[26:27]
	v_pk_fma_f32 v[148:149], v[148:149], v[12:13], v[28:29]
	v_pk_fma_f32 v[150:151], v[150:151], v[14:15], v[30:31]
	global_store_dwordx4 v176, v[136:139], s[8:9] offset:0
	global_store_dwordx4 v176, v[140:143], s[8:9] offset:1024
	global_store_dwordx4 v176, v[144:147], s[8:9] offset:2048
	global_store_dwordx4 v176, v[148:151], s[8:9] offset:3072
	s_add_u32 s8, s8, 0x1000
	s_addc_u32 s9, s9, 0
	s_add_u32 s12, s12, 0x800
	s_addc_u32 s13, s13, 0
	global_load_dwordx4 v[96:99], v176, s[14:15] offset:0
	global_load_dwordx4 v[100:103], v176, s[14:15] offset:1024
	global_load_dwordx4 v[104:107], v176, s[14:15] offset:2048
	global_load_dwordx4 v[108:111], v176, s[14:15] offset:3072
	global_load_dwordx2 v[128:129], v177, s[6:7] offset:0
	global_load_dwordx2 v[130:131], v177, s[6:7] offset:512
	global_load_dwordx2 v[132:133], v177, s[6:7] offset:1024
	global_load_dwordx2 v[134:135], v177, s[6:7] offset:1536
	s_add_u32 s14, s14, 0x1000
	s_addc_u32 s15, s15, 0
	s_add_u32 s6, s6, 0x800
	s_addc_u32 s7, s7, 0
	s_waitcnt vmcnt(24)
	v_lshlrev_b32_e32 v136, 16, v112
	v_and_b32_e32 v137, 0xffff0000, v112
	v_lshlrev_b32_e32 v138, 16, v113
	v_and_b32_e32 v139, 0xffff0000, v113
	v_lshlrev_b32_e32 v140, 16, v114
	v_and_b32_e32 v141, 0xffff0000, v114
	v_lshlrev_b32_e32 v142, 16, v115
	v_and_b32_e32 v143, 0xffff0000, v115
	v_lshlrev_b32_e32 v144, 16, v116
	v_and_b32_e32 v145, 0xffff0000, v116
	v_lshlrev_b32_e32 v146, 16, v117
	v_and_b32_e32 v147, 0xffff0000, v117
	v_lshlrev_b32_e32 v148, 16, v118
	v_and_b32_e32 v149, 0xffff0000, v118
	v_lshlrev_b32_e32 v150, 16, v119
	v_and_b32_e32 v151, 0xffff0000, v119
	v_pk_fma_f32 v[136:137], v[64:65], s[44:45], v[136:137]
	v_pk_fma_f32 v[138:139], v[66:67], s[44:45], v[138:139]
	v_pk_fma_f32 v[140:141], v[68:69], s[44:45], v[140:141]
	v_pk_fma_f32 v[142:143], v[70:71], s[44:45], v[142:143]
	v_pk_fma_f32 v[144:145], v[72:73], s[44:45], v[144:145]
	v_pk_fma_f32 v[146:147], v[74:75], s[44:45], v[146:147]
	v_pk_fma_f32 v[148:149], v[76:77], s[44:45], v[148:149]
	v_pk_fma_f32 v[150:151], v[78:79], s[44:45], v[150:151]
	v_pk_add_f32 v[152:153], v[136:137], v[138:139]
	v_pk_add_f32 v[152:153], v[152:153], v[140:141]
	v_pk_add_f32 v[152:153], v[152:153], v[142:143]
	v_pk_add_f32 v[152:153], v[152:153], v[144:145]
	v_pk_add_f32 v[152:153], v[152:153], v[146:147]
	v_pk_add_f32 v[152:153], v[152:153], v[148:149]
	v_pk_add_f32 v[152:153], v[152:153], v[150:151]
	v_add_f32_e32 v170, v152, v153
	s_nop 1
	v_add_f32_dpp v168, v170, v170 quad_perm:[1,0,3,2] row_mask:0xf bank_mask:0xf
	s_nop 1
	v_add_f32_dpp v168, v168, v168 quad_perm:[2,3,0,1] row_mask:0xf bank_mask:0xf
	s_nop 1
	v_add_f32_dpp v168, v168, v168 row_half_mirror row_mask:0xf bank_mask:0xf
	s_nop 1
	v_add_f32_dpp v168, v168, v168 row_mirror row_mask:0xf bank_mask:0xf
	s_nop 1
	v_add_f32_dpp v168, v168, v168 row_bcast:15 row_mask:0xa bank_mask:0xf
	s_nop 1
	v_add_f32_dpp v168, v168, v168 row_bcast:31 row_mask:0xc bank_mask:0xf
	s_nop 1
	v_readlane_b32 s42, v168, 63
	s_nop 3
	s_mov_b32 s43, s42
	v_pk_fma_f32 v[136:137], s[42:43], v[172:173], v[136:137]
	v_pk_fma_f32 v[138:139], s[42:43], v[172:173], v[138:139]
	v_pk_fma_f32 v[140:141], s[42:43], v[172:173], v[140:141]
	v_pk_fma_f32 v[142:143], s[42:43], v[172:173], v[142:143]
	v_pk_fma_f32 v[144:145], s[42:43], v[172:173], v[144:145]
	v_pk_fma_f32 v[146:147], s[42:43], v[172:173], v[146:147]
	v_pk_fma_f32 v[148:149], s[42:43], v[172:173], v[148:149]
	v_pk_fma_f32 v[150:151], s[42:43], v[172:173], v[150:151]
	v_pk_mul_f32 v[152:153], v[136:137], v[136:137]
	v_pk_fma_f32 v[152:153], v[138:139], v[138:139], v[152:153]
	v_pk_fma_f32 v[152:153], v[140:141], v[140:141], v[152:153]
	v_pk_fma_f32 v[152:153], v[142:143], v[142:143], v[152:153]
	v_pk_fma_f32 v[152:153], v[144:145], v[144:145], v[152:153]
	v_pk_fma_f32 v[152:153], v[146:147], v[146:147], v[152:153]
	v_pk_fma_f32 v[152:153], v[148:149], v[148:149], v[152:153]
	v_pk_fma_f32 v[152:153], v[150:151], v[150:151], v[152:153]
	v_add_f32_e32 v170, v152, v153
	s_nop 1
	v_add_f32_dpp v168, v170, v170 quad_perm:[1,0,3,2] row_mask:0xf bank_mask:0xf
	s_nop 1
	v_add_f32_dpp v168, v168, v168 quad_perm:[2,3,0,1] row_mask:0xf bank_mask:0xf
	s_nop 1
	v_add_f32_dpp v168, v168, v168 row_half_mirror row_mask:0xf bank_mask:0xf
	s_nop 1
	v_add_f32_dpp v168, v168, v168 row_mirror row_mask:0xf bank_mask:0xf
	s_nop 1
	v_add_f32_dpp v168, v168, v168 row_bcast:15 row_mask:0xa bank_mask:0xf
	s_nop 1
	v_add_f32_dpp v168, v168, v168 row_bcast:31 row_mask:0xc bank_mask:0xf
	s_nop 1
	v_readlane_b32 s42, v168, 63
	s_nop 3
	v_fma_f32 v174, s42, v178, v179
	v_rsq_f32_e32 v174, v174
	s_nop 0
	v_pk_mul_f32 v[136:137], v[136:137], v[174:175] op_sel_hi:[1,0]
	v_pk_mul_f32 v[138:139], v[138:139], v[174:175] op_sel_hi:[1,0]
	v_pk_mul_f32 v[140:141], v[140:141], v[174:175] op_sel_hi:[1,0]
	v_pk_mul_f32 v[142:143], v[142:143], v[174:175] op_sel_hi:[1,0]
	v_pk_mul_f32 v[144:145], v[144:145], v[174:175] op_sel_hi:[1,0]
	v_pk_mul_f32 v[146:147], v[146:147], v[174:175] op_sel_hi:[1,0]
	v_pk_mul_f32 v[148:149], v[148:149], v[174:175] op_sel_hi:[1,0]
	v_pk_mul_f32 v[150:151], v[150:151], v[174:175] op_sel_hi:[1,0]
	v_pk_fma_f32 v[136:137], v[136:137], v[0:1], v[16:17]
	v_pk_fma_f32 v[138:139], v[138:139], v[2:3], v[18:19]
	v_pk_fma_f32 v[140:141], v[140:141], v[4:5], v[20:21]
	v_pk_fma_f32 v[142:143], v[142:143], v[6:7], v[22:23]
	v_pk_fma_f32 v[144:145], v[144:145], v[8:9], v[24:25]
	v_pk_fma_f32 v[146:147], v[146:147], v[10:11], v[26:27]
	v_pk_fma_f32 v[148:149], v[148:149], v[12:13], v[28:29]
	v_pk_fma_f32 v[150:151], v[150:151], v[14:15], v[30:31]
	global_store_dwordx4 v176, v[136:139], s[8:9] offset:0
	global_store_dwordx4 v176, v[140:143], s[8:9] offset:1024
	global_store_dwordx4 v176, v[144:147], s[8:9] offset:2048
	global_store_dwordx4 v176, v[148:151], s[8:9] offset:3072
	s_add_u32 s8, s8, 0x1000
	s_addc_u32 s9, s9, 0
	s_add_u32 s12, s12, 0x800
	s_addc_u32 s13, s13, 0
	global_load_dwordx4 v[64:67], v176, s[14:15] offset:0
	global_load_dwordx4 v[68:71], v176, s[14:15] offset:1024
	global_load_dwordx4 v[72:75], v176, s[14:15] offset:2048
	global_load_dwordx4 v[76:79], v176, s[14:15] offset:3072
	global_load_dwordx2 v[112:113], v177, s[6:7] offset:0
	global_load_dwordx2 v[114:115], v177, s[6:7] offset:512
	global_load_dwordx2 v[116:117], v177, s[6:7] offset:1024
	global_load_dwordx2 v[118:119], v177, s[6:7] offset:1536
	s_add_u32 s14, s14, 0x1000
	s_addc_u32 s15, s15, 0
	s_add_u32 s6, s6, 0x800
	s_addc_u32 s7, s7, 0
	s_waitcnt vmcnt(24)
	v_lshlrev_b32_e32 v136, 16, v120
	v_and_b32_e32 v137, 0xffff0000, v120
	v_lshlrev_b32_e32 v138, 16, v121
	v_and_b32_e32 v139, 0xffff0000, v121
	v_lshlrev_b32_e32 v140, 16, v122
	v_and_b32_e32 v141, 0xffff0000, v122
	v_lshlrev_b32_e32 v142, 16, v123
	v_and_b32_e32 v143, 0xffff0000, v123
	v_lshlrev_b32_e32 v144, 16, v124
	v_and_b32_e32 v145, 0xffff0000, v124
	v_lshlrev_b32_e32 v146, 16, v125
	v_and_b32_e32 v147, 0xffff0000, v125
	v_lshlrev_b32_e32 v148, 16, v126
	v_and_b32_e32 v149, 0xffff0000, v126
	v_lshlrev_b32_e32 v150, 16, v127
	v_and_b32_e32 v151, 0xffff0000, v127
	v_pk_fma_f32 v[136:137], v[80:81], s[44:45], v[136:137]
	v_pk_fma_f32 v[138:139], v[82:83], s[44:45], v[138:139]
	v_pk_fma_f32 v[140:141], v[84:85], s[44:45], v[140:141]
	v_pk_fma_f32 v[142:143], v[86:87], s[44:45], v[142:143]
	v_pk_fma_f32 v[144:145], v[88:89], s[44:45], v[144:145]
	v_pk_fma_f32 v[146:147], v[90:91], s[44:45], v[146:147]
	v_pk_fma_f32 v[148:149], v[92:93], s[44:45], v[148:149]
	v_pk_fma_f32 v[150:151], v[94:95], s[44:45], v[150:151]
	v_pk_add_f32 v[152:153], v[136:137], v[138:139]
	v_pk_add_f32 v[152:153], v[152:153], v[140:141]
	v_pk_add_f32 v[152:153], v[152:153], v[142:143]
	v_pk_add_f32 v[152:153], v[152:153], v[144:145]
	v_pk_add_f32 v[152:153], v[152:153], v[146:147]
	v_pk_add_f32 v[152:153], v[152:153], v[148:149]
	v_pk_add_f32 v[152:153], v[152:153], v[150:151]
	v_add_f32_e32 v170, v152, v153
	s_nop 1
	v_add_f32_dpp v168, v170, v170 quad_perm:[1,0,3,2] row_mask:0xf bank_mask:0xf
	s_nop 1
	v_add_f32_dpp v168, v168, v168 quad_perm:[2,3,0,1] row_mask:0xf bank_mask:0xf
	s_nop 1
	v_add_f32_dpp v168, v168, v168 row_half_mirror row_mask:0xf bank_mask:0xf
	s_nop 1
	v_add_f32_dpp v168, v168, v168 row_mirror row_mask:0xf bank_mask:0xf
	s_nop 1
	v_add_f32_dpp v168, v168, v168 row_bcast:15 row_mask:0xa bank_mask:0xf
	s_nop 1
	v_add_f32_dpp v168, v168, v168 row_bcast:31 row_mask:0xc bank_mask:0xf
	s_nop 1
	v_readlane_b32 s42, v168, 63
	s_nop 3
	s_mov_b32 s43, s42
	v_pk_fma_f32 v[136:137], s[42:43], v[172:173], v[136:137]
	v_pk_fma_f32 v[138:139], s[42:43], v[172:173], v[138:139]
	v_pk_fma_f32 v[140:141], s[42:43], v[172:173], v[140:141]
	v_pk_fma_f32 v[142:143], s[42:43], v[172:173], v[142:143]
	v_pk_fma_f32 v[144:145], s[42:43], v[172:173], v[144:145]
	v_pk_fma_f32 v[146:147], s[42:43], v[172:173], v[146:147]
	v_pk_fma_f32 v[148:149], s[42:43], v[172:173], v[148:149]
	v_pk_fma_f32 v[150:151], s[42:43], v[172:173], v[150:151]
	v_pk_mul_f32 v[152:153], v[136:137], v[136:137]
	v_pk_fma_f32 v[152:153], v[138:139], v[138:139], v[152:153]
	v_pk_fma_f32 v[152:153], v[140:141], v[140:141], v[152:153]
	v_pk_fma_f32 v[152:153], v[142:143], v[142:143], v[152:153]
	v_pk_fma_f32 v[152:153], v[144:145], v[144:145], v[152:153]
	v_pk_fma_f32 v[152:153], v[146:147], v[146:147], v[152:153]
	v_pk_fma_f32 v[152:153], v[148:149], v[148:149], v[152:153]
	v_pk_fma_f32 v[152:153], v[150:151], v[150:151], v[152:153]
	v_add_f32_e32 v170, v152, v153
	s_nop 1
	v_add_f32_dpp v168, v170, v170 quad_perm:[1,0,3,2] row_mask:0xf bank_mask:0xf
	s_nop 1
	v_add_f32_dpp v168, v168, v168 quad_perm:[2,3,0,1] row_mask:0xf bank_mask:0xf
	s_nop 1
	v_add_f32_dpp v168, v168, v168 row_half_mirror row_mask:0xf bank_mask:0xf
	s_nop 1
	v_add_f32_dpp v168, v168, v168 row_mirror row_mask:0xf bank_mask:0xf
	s_nop 1
	v_add_f32_dpp v168, v168, v168 row_bcast:15 row_mask:0xa bank_mask:0xf
	s_nop 1
	v_add_f32_dpp v168, v168, v168 row_bcast:31 row_mask:0xc bank_mask:0xf
	s_nop 1
	v_readlane_b32 s42, v168, 63
	s_nop 3
	v_fma_f32 v174, s42, v178, v179
	v_rsq_f32_e32 v174, v174
	s_nop 0
	v_pk_mul_f32 v[136:137], v[136:137], v[174:175] op_sel_hi:[1,0]
	v_pk_mul_f32 v[138:139], v[138:139], v[174:175] op_sel_hi:[1,0]
	v_pk_mul_f32 v[140:141], v[140:141], v[174:175] op_sel_hi:[1,0]
	v_pk_mul_f32 v[142:143], v[142:143], v[174:175] op_sel_hi:[1,0]
	v_pk_mul_f32 v[144:145], v[144:145], v[174:175] op_sel_hi:[1,0]
	v_pk_mul_f32 v[146:147], v[146:147], v[174:175] op_sel_hi:[1,0]
	v_pk_mul_f32 v[148:149], v[148:149], v[174:175] op_sel_hi:[1,0]
	v_pk_mul_f32 v[150:151], v[150:151], v[174:175] op_sel_hi:[1,0]
	v_pk_fma_f32 v[136:137], v[136:137], v[0:1], v[16:17]
	v_pk_fma_f32 v[138:139], v[138:139], v[2:3], v[18:19]
	v_pk_fma_f32 v[140:141], v[140:141], v[4:5], v[20:21]
	v_pk_fma_f32 v[142:143], v[142:143], v[6:7], v[22:23]
	v_pk_fma_f32 v[144:145], v[144:145], v[8:9], v[24:25]
	v_pk_fma_f32 v[146:147], v[146:147], v[10:11], v[26:27]
	v_pk_fma_f32 v[148:149], v[148:149], v[12:13], v[28:29]
	v_pk_fma_f32 v[150:151], v[150:151], v[14:15], v[30:31]
	global_store_dwordx4 v176, v[136:139], s[8:9] offset:0
	global_store_dwordx4 v176, v[140:143], s[8:9] offset:1024
	global_store_dwordx4 v176, v[144:147], s[8:9] offset:2048
	global_store_dwordx4 v176, v[148:151], s[8:9] offset:3072
	s_add_u32 s8, s8, 0x1000
	s_addc_u32 s9, s9, 0
	s_add_u32 s12, s12, 0x800
	s_addc_u32 s13, s13, 0
	global_load_dwordx4 v[80:83], v176, s[14:15] offset:0
	global_load_dwordx4 v[84:87], v176, s[14:15] offset:1024
	global_load_dwordx4 v[88:91], v176, s[14:15] offset:2048
	global_load_dwordx4 v[92:95], v176, s[14:15] offset:3072
	global_load_dwordx2 v[120:121], v177, s[6:7] offset:0
	global_load_dwordx2 v[122:123], v177, s[6:7] offset:512
	global_load_dwordx2 v[124:125], v177, s[6:7] offset:1024
	global_load_dwordx2 v[126:127], v177, s[6:7] offset:1536
	s_add_u32 s14, s14, 0x1000
	s_addc_u32 s15, s15, 0
	s_add_u32 s6, s6, 0x800
	s_addc_u32 s7, s7, 0
	s_waitcnt vmcnt(24)
	v_lshlrev_b32_e32 v136, 16, v128
	v_and_b32_e32 v137, 0xffff0000, v128
	v_lshlrev_b32_e32 v138, 16, v129
	v_and_b32_e32 v139, 0xffff0000, v129
	v_lshlrev_b32_e32 v140, 16, v130
	v_and_b32_e32 v141, 0xffff0000, v130
	v_lshlrev_b32_e32 v142, 16, v131
	v_and_b32_e32 v143, 0xffff0000, v131
	v_lshlrev_b32_e32 v144, 16, v132
	v_and_b32_e32 v145, 0xffff0000, v132
	v_lshlrev_b32_e32 v146, 16, v133
	v_and_b32_e32 v147, 0xffff0000, v133
	v_lshlrev_b32_e32 v148, 16, v134
	v_and_b32_e32 v149, 0xffff0000, v134
	v_lshlrev_b32_e32 v150, 16, v135
	v_and_b32_e32 v151, 0xffff0000, v135
	v_pk_fma_f32 v[136:137], v[96:97], s[44:45], v[136:137]
	v_pk_fma_f32 v[138:139], v[98:99], s[44:45], v[138:139]
	v_pk_fma_f32 v[140:141], v[100:101], s[44:45], v[140:141]
	v_pk_fma_f32 v[142:143], v[102:103], s[44:45], v[142:143]
	v_pk_fma_f32 v[144:145], v[104:105], s[44:45], v[144:145]
	v_pk_fma_f32 v[146:147], v[106:107], s[44:45], v[146:147]
	v_pk_fma_f32 v[148:149], v[108:109], s[44:45], v[148:149]
	v_pk_fma_f32 v[150:151], v[110:111], s[44:45], v[150:151]
	v_pk_add_f32 v[152:153], v[136:137], v[138:139]
	v_pk_add_f32 v[152:153], v[152:153], v[140:141]
	v_pk_add_f32 v[152:153], v[152:153], v[142:143]
	v_pk_add_f32 v[152:153], v[152:153], v[144:145]
	v_pk_add_f32 v[152:153], v[152:153], v[146:147]
	v_pk_add_f32 v[152:153], v[152:153], v[148:149]
	v_pk_add_f32 v[152:153], v[152:153], v[150:151]
	v_add_f32_e32 v170, v152, v153
	s_nop 1
	v_add_f32_dpp v168, v170, v170 quad_perm:[1,0,3,2] row_mask:0xf bank_mask:0xf
	s_nop 1
	v_add_f32_dpp v168, v168, v168 quad_perm:[2,3,0,1] row_mask:0xf bank_mask:0xf
	s_nop 1
	v_add_f32_dpp v168, v168, v168 row_half_mirror row_mask:0xf bank_mask:0xf
	s_nop 1
	v_add_f32_dpp v168, v168, v168 row_mirror row_mask:0xf bank_mask:0xf
	s_nop 1
	v_add_f32_dpp v168, v168, v168 row_bcast:15 row_mask:0xa bank_mask:0xf
	s_nop 1
	v_add_f32_dpp v168, v168, v168 row_bcast:31 row_mask:0xc bank_mask:0xf
	s_nop 1
	v_readlane_b32 s42, v168, 63
	s_nop 3
	s_mov_b32 s43, s42
	v_pk_fma_f32 v[136:137], s[42:43], v[172:173], v[136:137]
	v_pk_fma_f32 v[138:139], s[42:43], v[172:173], v[138:139]
	v_pk_fma_f32 v[140:141], s[42:43], v[172:173], v[140:141]
	v_pk_fma_f32 v[142:143], s[42:43], v[172:173], v[142:143]
	v_pk_fma_f32 v[144:145], s[42:43], v[172:173], v[144:145]
	v_pk_fma_f32 v[146:147], s[42:43], v[172:173], v[146:147]
	v_pk_fma_f32 v[148:149], s[42:43], v[172:173], v[148:149]
	v_pk_fma_f32 v[150:151], s[42:43], v[172:173], v[150:151]
	v_pk_mul_f32 v[152:153], v[136:137], v[136:137]
	v_pk_fma_f32 v[152:153], v[138:139], v[138:139], v[152:153]
	v_pk_fma_f32 v[152:153], v[140:141], v[140:141], v[152:153]
	v_pk_fma_f32 v[152:153], v[142:143], v[142:143], v[152:153]
	v_pk_fma_f32 v[152:153], v[144:145], v[144:145], v[152:153]
	v_pk_fma_f32 v[152:153], v[146:147], v[146:147], v[152:153]
	v_pk_fma_f32 v[152:153], v[148:149], v[148:149], v[152:153]
	v_pk_fma_f32 v[152:153], v[150:151], v[150:151], v[152:153]
	v_add_f32_e32 v170, v152, v153
	s_nop 1
	v_add_f32_dpp v168, v170, v170 quad_perm:[1,0,3,2] row_mask:0xf bank_mask:0xf
	s_nop 1
	v_add_f32_dpp v168, v168, v168 quad_perm:[2,3,0,1] row_mask:0xf bank_mask:0xf
	s_nop 1
	v_add_f32_dpp v168, v168, v168 row_half_mirror row_mask:0xf bank_mask:0xf
	s_nop 1
	v_add_f32_dpp v168, v168, v168 row_mirror row_mask:0xf bank_mask:0xf
	s_nop 1
	v_add_f32_dpp v168, v168, v168 row_bcast:15 row_mask:0xa bank_mask:0xf
	s_nop 1
	v_add_f32_dpp v168, v168, v168 row_bcast:31 row_mask:0xc bank_mask:0xf
	s_nop 1
	v_readlane_b32 s42, v168, 63
	s_nop 3
	v_fma_f32 v174, s42, v178, v179
	v_rsq_f32_e32 v174, v174
	s_nop 0
	v_pk_mul_f32 v[136:137], v[136:137], v[174:175] op_sel_hi:[1,0]
	v_pk_mul_f32 v[138:139], v[138:139], v[174:175] op_sel_hi:[1,0]
	v_pk_mul_f32 v[140:141], v[140:141], v[174:175] op_sel_hi:[1,0]
	v_pk_mul_f32 v[142:143], v[142:143], v[174:175] op_sel_hi:[1,0]
	v_pk_mul_f32 v[144:145], v[144:145], v[174:175] op_sel_hi:[1,0]
	v_pk_mul_f32 v[146:147], v[146:147], v[174:175] op_sel_hi:[1,0]
	v_pk_mul_f32 v[148:149], v[148:149], v[174:175] op_sel_hi:[1,0]
	v_pk_mul_f32 v[150:151], v[150:151], v[174:175] op_sel_hi:[1,0]
	v_pk_fma_f32 v[136:137], v[136:137], v[0:1], v[16:17]
	v_pk_fma_f32 v[138:139], v[138:139], v[2:3], v[18:19]
	v_pk_fma_f32 v[140:141], v[140:141], v[4:5], v[20:21]
	v_pk_fma_f32 v[142:143], v[142:143], v[6:7], v[22:23]
	v_pk_fma_f32 v[144:145], v[144:145], v[8:9], v[24:25]
	v_pk_fma_f32 v[146:147], v[146:147], v[10:11], v[26:27]
	v_pk_fma_f32 v[148:149], v[148:149], v[12:13], v[28:29]
	v_pk_fma_f32 v[150:151], v[150:151], v[14:15], v[30:31]
	global_store_dwordx4 v176, v[136:139], s[8:9] offset:0
	global_store_dwordx4 v176, v[140:143], s[8:9] offset:1024
	global_store_dwordx4 v176, v[144:147], s[8:9] offset:2048
	global_store_dwordx4 v176, v[148:151], s[8:9] offset:3072
	s_add_u32 s8, s8, 0x1000
	s_addc_u32 s9, s9, 0
	s_add_u32 s12, s12, 0x800
	s_addc_u32 s13, s13, 0
	global_load_dwordx4 v[96:99], v176, s[14:15] offset:0
	global_load_dwordx4 v[100:103], v176, s[14:15] offset:1024
	global_load_dwordx4 v[104:107], v176, s[14:15] offset:2048
	global_load_dwordx4 v[108:111], v176, s[14:15] offset:3072
	global_load_dwordx2 v[128:129], v177, s[6:7] offset:0
	global_load_dwordx2 v[130:131], v177, s[6:7] offset:512
	global_load_dwordx2 v[132:133], v177, s[6:7] offset:1024
	global_load_dwordx2 v[134:135], v177, s[6:7] offset:1536
	s_add_u32 s14, s14, 0x1000
	s_addc_u32 s15, s15, 0
	s_add_u32 s6, s6, 0x800
	s_addc_u32 s7, s7, 0
	s_waitcnt vmcnt(24)
	v_lshlrev_b32_e32 v136, 16, v112
	v_and_b32_e32 v137, 0xffff0000, v112
	v_lshlrev_b32_e32 v138, 16, v113
	v_and_b32_e32 v139, 0xffff0000, v113
	v_lshlrev_b32_e32 v140, 16, v114
	v_and_b32_e32 v141, 0xffff0000, v114
	v_lshlrev_b32_e32 v142, 16, v115
	v_and_b32_e32 v143, 0xffff0000, v115
	v_lshlrev_b32_e32 v144, 16, v116
	v_and_b32_e32 v145, 0xffff0000, v116
	v_lshlrev_b32_e32 v146, 16, v117
	v_and_b32_e32 v147, 0xffff0000, v117
	v_lshlrev_b32_e32 v148, 16, v118
	v_and_b32_e32 v149, 0xffff0000, v118
	v_lshlrev_b32_e32 v150, 16, v119
	v_and_b32_e32 v151, 0xffff0000, v119
	v_pk_fma_f32 v[136:137], v[64:65], s[44:45], v[136:137]
	v_pk_fma_f32 v[138:139], v[66:67], s[44:45], v[138:139]
	v_pk_fma_f32 v[140:141], v[68:69], s[44:45], v[140:141]
	v_pk_fma_f32 v[142:143], v[70:71], s[44:45], v[142:143]
	v_pk_fma_f32 v[144:145], v[72:73], s[44:45], v[144:145]
	v_pk_fma_f32 v[146:147], v[74:75], s[44:45], v[146:147]
	v_pk_fma_f32 v[148:149], v[76:77], s[44:45], v[148:149]
	v_pk_fma_f32 v[150:151], v[78:79], s[44:45], v[150:151]
	v_pk_add_f32 v[152:153], v[136:137], v[138:139]
	v_pk_add_f32 v[152:153], v[152:153], v[140:141]
	v_pk_add_f32 v[152:153], v[152:153], v[142:143]
	v_pk_add_f32 v[152:153], v[152:153], v[144:145]
	v_pk_add_f32 v[152:153], v[152:153], v[146:147]
	v_pk_add_f32 v[152:153], v[152:153], v[148:149]
	v_pk_add_f32 v[152:153], v[152:153], v[150:151]
	v_add_f32_e32 v170, v152, v153
	s_nop 1
	v_add_f32_dpp v168, v170, v170 quad_perm:[1,0,3,2] row_mask:0xf bank_mask:0xf
	s_nop 1
	v_add_f32_dpp v168, v168, v168 quad_perm:[2,3,0,1] row_mask:0xf bank_mask:0xf
	s_nop 1
	v_add_f32_dpp v168, v168, v168 row_half_mirror row_mask:0xf bank_mask:0xf
	s_nop 1
	v_add_f32_dpp v168, v168, v168 row_mirror row_mask:0xf bank_mask:0xf
	s_nop 1
	v_add_f32_dpp v168, v168, v168 row_bcast:15 row_mask:0xa bank_mask:0xf
	s_nop 1
	v_add_f32_dpp v168, v168, v168 row_bcast:31 row_mask:0xc bank_mask:0xf
	s_nop 1
	v_readlane_b32 s42, v168, 63
	s_nop 3
	s_mov_b32 s43, s42
	v_pk_fma_f32 v[136:137], s[42:43], v[172:173], v[136:137]
	v_pk_fma_f32 v[138:139], s[42:43], v[172:173], v[138:139]
	v_pk_fma_f32 v[140:141], s[42:43], v[172:173], v[140:141]
	v_pk_fma_f32 v[142:143], s[42:43], v[172:173], v[142:143]
	v_pk_fma_f32 v[144:145], s[42:43], v[172:173], v[144:145]
	v_pk_fma_f32 v[146:147], s[42:43], v[172:173], v[146:147]
	v_pk_fma_f32 v[148:149], s[42:43], v[172:173], v[148:149]
	v_pk_fma_f32 v[150:151], s[42:43], v[172:173], v[150:151]
	v_pk_mul_f32 v[152:153], v[136:137], v[136:137]
	v_pk_fma_f32 v[152:153], v[138:139], v[138:139], v[152:153]
	v_pk_fma_f32 v[152:153], v[140:141], v[140:141], v[152:153]
	v_pk_fma_f32 v[152:153], v[142:143], v[142:143], v[152:153]
	v_pk_fma_f32 v[152:153], v[144:145], v[144:145], v[152:153]
	v_pk_fma_f32 v[152:153], v[146:147], v[146:147], v[152:153]
	v_pk_fma_f32 v[152:153], v[148:149], v[148:149], v[152:153]
	v_pk_fma_f32 v[152:153], v[150:151], v[150:151], v[152:153]
	v_add_f32_e32 v170, v152, v153
	s_nop 1
	v_add_f32_dpp v168, v170, v170 quad_perm:[1,0,3,2] row_mask:0xf bank_mask:0xf
	s_nop 1
	v_add_f32_dpp v168, v168, v168 quad_perm:[2,3,0,1] row_mask:0xf bank_mask:0xf
	s_nop 1
	v_add_f32_dpp v168, v168, v168 row_half_mirror row_mask:0xf bank_mask:0xf
	s_nop 1
	v_add_f32_dpp v168, v168, v168 row_mirror row_mask:0xf bank_mask:0xf
	s_nop 1
	v_add_f32_dpp v168, v168, v168 row_bcast:15 row_mask:0xa bank_mask:0xf
	s_nop 1
	v_add_f32_dpp v168, v168, v168 row_bcast:31 row_mask:0xc bank_mask:0xf
	s_nop 1
	v_readlane_b32 s42, v168, 63
	s_nop 3
	v_fma_f32 v174, s42, v178, v179
	v_rsq_f32_e32 v174, v174
	s_nop 0
	v_pk_mul_f32 v[136:137], v[136:137], v[174:175] op_sel_hi:[1,0]
	v_pk_mul_f32 v[138:139], v[138:139], v[174:175] op_sel_hi:[1,0]
	v_pk_mul_f32 v[140:141], v[140:141], v[174:175] op_sel_hi:[1,0]
	v_pk_mul_f32 v[142:143], v[142:143], v[174:175] op_sel_hi:[1,0]
	v_pk_mul_f32 v[144:145], v[144:145], v[174:175] op_sel_hi:[1,0]
	v_pk_mul_f32 v[146:147], v[146:147], v[174:175] op_sel_hi:[1,0]
	v_pk_mul_f32 v[148:149], v[148:149], v[174:175] op_sel_hi:[1,0]
	v_pk_mul_f32 v[150:151], v[150:151], v[174:175] op_sel_hi:[1,0]
	v_pk_fma_f32 v[136:137], v[136:137], v[0:1], v[16:17]
	v_pk_fma_f32 v[138:139], v[138:139], v[2:3], v[18:19]
	v_pk_fma_f32 v[140:141], v[140:141], v[4:5], v[20:21]
	v_pk_fma_f32 v[142:143], v[142:143], v[6:7], v[22:23]
	v_pk_fma_f32 v[144:145], v[144:145], v[8:9], v[24:25]
	v_pk_fma_f32 v[146:147], v[146:147], v[10:11], v[26:27]
	v_pk_fma_f32 v[148:149], v[148:149], v[12:13], v[28:29]
	v_pk_fma_f32 v[150:151], v[150:151], v[14:15], v[30:31]
	global_store_dwordx4 v176, v[136:139], s[8:9] offset:0
	global_store_dwordx4 v176, v[140:143], s[8:9] offset:1024
	global_store_dwordx4 v176, v[144:147], s[8:9] offset:2048
	global_store_dwordx4 v176, v[148:151], s[8:9] offset:3072
	s_add_u32 s8, s8, 0x1000
	s_addc_u32 s9, s9, 0
	s_add_u32 s12, s12, 0x800
	s_addc_u32 s13, s13, 0
	global_load_dwordx4 v[64:67], v176, s[14:15] offset:0
	global_load_dwordx4 v[68:71], v176, s[14:15] offset:1024
	global_load_dwordx4 v[72:75], v176, s[14:15] offset:2048
	global_load_dwordx4 v[76:79], v176, s[14:15] offset:3072
	global_load_dwordx2 v[112:113], v177, s[6:7] offset:0
	global_load_dwordx2 v[114:115], v177, s[6:7] offset:512
	global_load_dwordx2 v[116:117], v177, s[6:7] offset:1024
	global_load_dwordx2 v[118:119], v177, s[6:7] offset:1536
	s_add_u32 s14, s14, 0x1000
	s_addc_u32 s15, s15, 0
	s_add_u32 s6, s6, 0x800
	s_addc_u32 s7, s7, 0
	s_waitcnt vmcnt(24)
	v_lshlrev_b32_e32 v136, 16, v120
	v_and_b32_e32 v137, 0xffff0000, v120
	v_lshlrev_b32_e32 v138, 16, v121
	v_and_b32_e32 v139, 0xffff0000, v121
	v_lshlrev_b32_e32 v140, 16, v122
	v_and_b32_e32 v141, 0xffff0000, v122
	v_lshlrev_b32_e32 v142, 16, v123
	v_and_b32_e32 v143, 0xffff0000, v123
	v_lshlrev_b32_e32 v144, 16, v124
	v_and_b32_e32 v145, 0xffff0000, v124
	v_lshlrev_b32_e32 v146, 16, v125
	v_and_b32_e32 v147, 0xffff0000, v125
	v_lshlrev_b32_e32 v148, 16, v126
	v_and_b32_e32 v149, 0xffff0000, v126
	v_lshlrev_b32_e32 v150, 16, v127
	v_and_b32_e32 v151, 0xffff0000, v127
	v_pk_fma_f32 v[136:137], v[80:81], s[44:45], v[136:137]
	v_pk_fma_f32 v[138:139], v[82:83], s[44:45], v[138:139]
	v_pk_fma_f32 v[140:141], v[84:85], s[44:45], v[140:141]
	v_pk_fma_f32 v[142:143], v[86:87], s[44:45], v[142:143]
	v_pk_fma_f32 v[144:145], v[88:89], s[44:45], v[144:145]
	v_pk_fma_f32 v[146:147], v[90:91], s[44:45], v[146:147]
	v_pk_fma_f32 v[148:149], v[92:93], s[44:45], v[148:149]
	v_pk_fma_f32 v[150:151], v[94:95], s[44:45], v[150:151]
	v_pk_add_f32 v[152:153], v[136:137], v[138:139]
	v_pk_add_f32 v[152:153], v[152:153], v[140:141]
	v_pk_add_f32 v[152:153], v[152:153], v[142:143]
	v_pk_add_f32 v[152:153], v[152:153], v[144:145]
	v_pk_add_f32 v[152:153], v[152:153], v[146:147]
	v_pk_add_f32 v[152:153], v[152:153], v[148:149]
	v_pk_add_f32 v[152:153], v[152:153], v[150:151]
	v_add_f32_e32 v170, v152, v153
	s_nop 1
	v_add_f32_dpp v168, v170, v170 quad_perm:[1,0,3,2] row_mask:0xf bank_mask:0xf
	s_nop 1
	v_add_f32_dpp v168, v168, v168 quad_perm:[2,3,0,1] row_mask:0xf bank_mask:0xf
	s_nop 1
	v_add_f32_dpp v168, v168, v168 row_half_mirror row_mask:0xf bank_mask:0xf
	s_nop 1
	v_add_f32_dpp v168, v168, v168 row_mirror row_mask:0xf bank_mask:0xf
	s_nop 1
	v_add_f32_dpp v168, v168, v168 row_bcast:15 row_mask:0xa bank_mask:0xf
	s_nop 1
	v_add_f32_dpp v168, v168, v168 row_bcast:31 row_mask:0xc bank_mask:0xf
	s_nop 1
	v_readlane_b32 s42, v168, 63
	s_nop 3
	s_mov_b32 s43, s42
	v_pk_fma_f32 v[136:137], s[42:43], v[172:173], v[136:137]
	v_pk_fma_f32 v[138:139], s[42:43], v[172:173], v[138:139]
	v_pk_fma_f32 v[140:141], s[42:43], v[172:173], v[140:141]
	v_pk_fma_f32 v[142:143], s[42:43], v[172:173], v[142:143]
	v_pk_fma_f32 v[144:145], s[42:43], v[172:173], v[144:145]
	v_pk_fma_f32 v[146:147], s[42:43], v[172:173], v[146:147]
	v_pk_fma_f32 v[148:149], s[42:43], v[172:173], v[148:149]
	v_pk_fma_f32 v[150:151], s[42:43], v[172:173], v[150:151]
	v_pk_mul_f32 v[152:153], v[136:137], v[136:137]
	v_pk_fma_f32 v[152:153], v[138:139], v[138:139], v[152:153]
	v_pk_fma_f32 v[152:153], v[140:141], v[140:141], v[152:153]
	v_pk_fma_f32 v[152:153], v[142:143], v[142:143], v[152:153]
	v_pk_fma_f32 v[152:153], v[144:145], v[144:145], v[152:153]
	v_pk_fma_f32 v[152:153], v[146:147], v[146:147], v[152:153]
	v_pk_fma_f32 v[152:153], v[148:149], v[148:149], v[152:153]
	v_pk_fma_f32 v[152:153], v[150:151], v[150:151], v[152:153]
	v_add_f32_e32 v170, v152, v153
	s_nop 1
	v_add_f32_dpp v168, v170, v170 quad_perm:[1,0,3,2] row_mask:0xf bank_mask:0xf
	s_nop 1
	v_add_f32_dpp v168, v168, v168 quad_perm:[2,3,0,1] row_mask:0xf bank_mask:0xf
	s_nop 1
	v_add_f32_dpp v168, v168, v168 row_half_mirror row_mask:0xf bank_mask:0xf
	s_nop 1
	v_add_f32_dpp v168, v168, v168 row_mirror row_mask:0xf bank_mask:0xf
	s_nop 1
	v_add_f32_dpp v168, v168, v168 row_bcast:15 row_mask:0xa bank_mask:0xf
	s_nop 1
	v_add_f32_dpp v168, v168, v168 row_bcast:31 row_mask:0xc bank_mask:0xf
	s_nop 1
	v_readlane_b32 s42, v168, 63
	s_nop 3
	v_fma_f32 v174, s42, v178, v179
	v_rsq_f32_e32 v174, v174
	s_nop 0
	v_pk_mul_f32 v[136:137], v[136:137], v[174:175] op_sel_hi:[1,0]
	v_pk_mul_f32 v[138:139], v[138:139], v[174:175] op_sel_hi:[1,0]
	v_pk_mul_f32 v[140:141], v[140:141], v[174:175] op_sel_hi:[1,0]
	v_pk_mul_f32 v[142:143], v[142:143], v[174:175] op_sel_hi:[1,0]
	v_pk_mul_f32 v[144:145], v[144:145], v[174:175] op_sel_hi:[1,0]
	v_pk_mul_f32 v[146:147], v[146:147], v[174:175] op_sel_hi:[1,0]
	v_pk_mul_f32 v[148:149], v[148:149], v[174:175] op_sel_hi:[1,0]
	v_pk_mul_f32 v[150:151], v[150:151], v[174:175] op_sel_hi:[1,0]
	v_pk_fma_f32 v[136:137], v[136:137], v[0:1], v[16:17]
	v_pk_fma_f32 v[138:139], v[138:139], v[2:3], v[18:19]
	v_pk_fma_f32 v[140:141], v[140:141], v[4:5], v[20:21]
	v_pk_fma_f32 v[142:143], v[142:143], v[6:7], v[22:23]
	v_pk_fma_f32 v[144:145], v[144:145], v[8:9], v[24:25]
	v_pk_fma_f32 v[146:147], v[146:147], v[10:11], v[26:27]
	v_pk_fma_f32 v[148:149], v[148:149], v[12:13], v[28:29]
	v_pk_fma_f32 v[150:151], v[150:151], v[14:15], v[30:31]
	global_store_dwordx4 v176, v[136:139], s[8:9] offset:0
	global_store_dwordx4 v176, v[140:143], s[8:9] offset:1024
	global_store_dwordx4 v176, v[144:147], s[8:9] offset:2048
	global_store_dwordx4 v176, v[148:151], s[8:9] offset:3072
	s_add_u32 s8, s8, 0x1000
	s_addc_u32 s9, s9, 0
	s_add_u32 s12, s12, 0x800
	s_addc_u32 s13, s13, 0
	global_load_dwordx4 v[80:83], v176, s[14:15] offset:0
	global_load_dwordx4 v[84:87], v176, s[14:15] offset:1024
	global_load_dwordx4 v[88:91], v176, s[14:15] offset:2048
	global_load_dwordx4 v[92:95], v176, s[14:15] offset:3072
	global_load_dwordx2 v[120:121], v177, s[6:7] offset:0
	global_load_dwordx2 v[122:123], v177, s[6:7] offset:512
	global_load_dwordx2 v[124:125], v177, s[6:7] offset:1024
	global_load_dwordx2 v[126:127], v177, s[6:7] offset:1536
	s_add_u32 s14, s14, 0x1000
	s_addc_u32 s15, s15, 0
	s_add_u32 s6, s6, 0x800
	s_addc_u32 s7, s7, 0
	s_waitcnt vmcnt(24)
	v_lshlrev_b32_e32 v136, 16, v128
	v_and_b32_e32 v137, 0xffff0000, v128
	v_lshlrev_b32_e32 v138, 16, v129
	v_and_b32_e32 v139, 0xffff0000, v129
	v_lshlrev_b32_e32 v140, 16, v130
	v_and_b32_e32 v141, 0xffff0000, v130
	v_lshlrev_b32_e32 v142, 16, v131
	v_and_b32_e32 v143, 0xffff0000, v131
	v_lshlrev_b32_e32 v144, 16, v132
	v_and_b32_e32 v145, 0xffff0000, v132
	v_lshlrev_b32_e32 v146, 16, v133
	v_and_b32_e32 v147, 0xffff0000, v133
	v_lshlrev_b32_e32 v148, 16, v134
	v_and_b32_e32 v149, 0xffff0000, v134
	v_lshlrev_b32_e32 v150, 16, v135
	v_and_b32_e32 v151, 0xffff0000, v135
	v_pk_fma_f32 v[136:137], v[96:97], s[44:45], v[136:137]
	v_pk_fma_f32 v[138:139], v[98:99], s[44:45], v[138:139]
	v_pk_fma_f32 v[140:141], v[100:101], s[44:45], v[140:141]
	v_pk_fma_f32 v[142:143], v[102:103], s[44:45], v[142:143]
	v_pk_fma_f32 v[144:145], v[104:105], s[44:45], v[144:145]
	v_pk_fma_f32 v[146:147], v[106:107], s[44:45], v[146:147]
	v_pk_fma_f32 v[148:149], v[108:109], s[44:45], v[148:149]
	v_pk_fma_f32 v[150:151], v[110:111], s[44:45], v[150:151]
	v_pk_add_f32 v[152:153], v[136:137], v[138:139]
	v_pk_add_f32 v[152:153], v[152:153], v[140:141]
	v_pk_add_f32 v[152:153], v[152:153], v[142:143]
	v_pk_add_f32 v[152:153], v[152:153], v[144:145]
	v_pk_add_f32 v[152:153], v[152:153], v[146:147]
	v_pk_add_f32 v[152:153], v[152:153], v[148:149]
	v_pk_add_f32 v[152:153], v[152:153], v[150:151]
	v_add_f32_e32 v170, v152, v153
	s_nop 1
	v_add_f32_dpp v168, v170, v170 quad_perm:[1,0,3,2] row_mask:0xf bank_mask:0xf
	s_nop 1
	v_add_f32_dpp v168, v168, v168 quad_perm:[2,3,0,1] row_mask:0xf bank_mask:0xf
	s_nop 1
	v_add_f32_dpp v168, v168, v168 row_half_mirror row_mask:0xf bank_mask:0xf
	s_nop 1
	v_add_f32_dpp v168, v168, v168 row_mirror row_mask:0xf bank_mask:0xf
	s_nop 1
	v_add_f32_dpp v168, v168, v168 row_bcast:15 row_mask:0xa bank_mask:0xf
	s_nop 1
	v_add_f32_dpp v168, v168, v168 row_bcast:31 row_mask:0xc bank_mask:0xf
	s_nop 1
	v_readlane_b32 s42, v168, 63
	s_nop 3
	s_mov_b32 s43, s42
	v_pk_fma_f32 v[136:137], s[42:43], v[172:173], v[136:137]
	v_pk_fma_f32 v[138:139], s[42:43], v[172:173], v[138:139]
	v_pk_fma_f32 v[140:141], s[42:43], v[172:173], v[140:141]
	v_pk_fma_f32 v[142:143], s[42:43], v[172:173], v[142:143]
	v_pk_fma_f32 v[144:145], s[42:43], v[172:173], v[144:145]
	v_pk_fma_f32 v[146:147], s[42:43], v[172:173], v[146:147]
	v_pk_fma_f32 v[148:149], s[42:43], v[172:173], v[148:149]
	v_pk_fma_f32 v[150:151], s[42:43], v[172:173], v[150:151]
	v_pk_mul_f32 v[152:153], v[136:137], v[136:137]
	v_pk_fma_f32 v[152:153], v[138:139], v[138:139], v[152:153]
	v_pk_fma_f32 v[152:153], v[140:141], v[140:141], v[152:153]
	v_pk_fma_f32 v[152:153], v[142:143], v[142:143], v[152:153]
	v_pk_fma_f32 v[152:153], v[144:145], v[144:145], v[152:153]
	v_pk_fma_f32 v[152:153], v[146:147], v[146:147], v[152:153]
	v_pk_fma_f32 v[152:153], v[148:149], v[148:149], v[152:153]
	v_pk_fma_f32 v[152:153], v[150:151], v[150:151], v[152:153]
	v_add_f32_e32 v170, v152, v153
	s_nop 1
	v_add_f32_dpp v168, v170, v170 quad_perm:[1,0,3,2] row_mask:0xf bank_mask:0xf
	s_nop 1
	v_add_f32_dpp v168, v168, v168 quad_perm:[2,3,0,1] row_mask:0xf bank_mask:0xf
	s_nop 1
	v_add_f32_dpp v168, v168, v168 row_half_mirror row_mask:0xf bank_mask:0xf
	s_nop 1
	v_add_f32_dpp v168, v168, v168 row_mirror row_mask:0xf bank_mask:0xf
	s_nop 1
	v_add_f32_dpp v168, v168, v168 row_bcast:15 row_mask:0xa bank_mask:0xf
	s_nop 1
	v_add_f32_dpp v168, v168, v168 row_bcast:31 row_mask:0xc bank_mask:0xf
	s_nop 1
	v_readlane_b32 s42, v168, 63
	s_nop 3
	v_fma_f32 v174, s42, v178, v179
	v_rsq_f32_e32 v174, v174
	s_nop 0
	v_pk_mul_f32 v[136:137], v[136:137], v[174:175] op_sel_hi:[1,0]
	v_pk_mul_f32 v[138:139], v[138:139], v[174:175] op_sel_hi:[1,0]
	v_pk_mul_f32 v[140:141], v[140:141], v[174:175] op_sel_hi:[1,0]
	v_pk_mul_f32 v[142:143], v[142:143], v[174:175] op_sel_hi:[1,0]
	v_pk_mul_f32 v[144:145], v[144:145], v[174:175] op_sel_hi:[1,0]
	v_pk_mul_f32 v[146:147], v[146:147], v[174:175] op_sel_hi:[1,0]
	v_pk_mul_f32 v[148:149], v[148:149], v[174:175] op_sel_hi:[1,0]
	v_pk_mul_f32 v[150:151], v[150:151], v[174:175] op_sel_hi:[1,0]
	v_pk_fma_f32 v[136:137], v[136:137], v[0:1], v[16:17]
	v_pk_fma_f32 v[138:139], v[138:139], v[2:3], v[18:19]
	v_pk_fma_f32 v[140:141], v[140:141], v[4:5], v[20:21]
	v_pk_fma_f32 v[142:143], v[142:143], v[6:7], v[22:23]
	v_pk_fma_f32 v[144:145], v[144:145], v[8:9], v[24:25]
	v_pk_fma_f32 v[146:147], v[146:147], v[10:11], v[26:27]
	v_pk_fma_f32 v[148:149], v[148:149], v[12:13], v[28:29]
	v_pk_fma_f32 v[150:151], v[150:151], v[14:15], v[30:31]
	global_store_dwordx4 v176, v[136:139], s[8:9] offset:0
	global_store_dwordx4 v176, v[140:143], s[8:9] offset:1024
	global_store_dwordx4 v176, v[144:147], s[8:9] offset:2048
	global_store_dwordx4 v176, v[148:151], s[8:9] offset:3072
	s_add_u32 s8, s8, 0x1000
	s_addc_u32 s9, s9, 0
	s_add_u32 s12, s12, 0x800
	s_addc_u32 s13, s13, 0
	global_load_dwordx4 v[96:99], v176, s[14:15] offset:0
	global_load_dwordx4 v[100:103], v176, s[14:15] offset:1024
	global_load_dwordx4 v[104:107], v176, s[14:15] offset:2048
	global_load_dwordx4 v[108:111], v176, s[14:15] offset:3072
	global_load_dwordx2 v[128:129], v177, s[6:7] offset:0
	global_load_dwordx2 v[130:131], v177, s[6:7] offset:512
	global_load_dwordx2 v[132:133], v177, s[6:7] offset:1024
	global_load_dwordx2 v[134:135], v177, s[6:7] offset:1536
	s_add_u32 s14, s14, 0x1000
	s_addc_u32 s15, s15, 0
	s_add_u32 s6, s6, 0x800
	s_addc_u32 s7, s7, 0
	s_waitcnt vmcnt(24)
	v_lshlrev_b32_e32 v136, 16, v112
	v_and_b32_e32 v137, 0xffff0000, v112
	v_lshlrev_b32_e32 v138, 16, v113
	v_and_b32_e32 v139, 0xffff0000, v113
	v_lshlrev_b32_e32 v140, 16, v114
	v_and_b32_e32 v141, 0xffff0000, v114
	v_lshlrev_b32_e32 v142, 16, v115
	v_and_b32_e32 v143, 0xffff0000, v115
	v_lshlrev_b32_e32 v144, 16, v116
	v_and_b32_e32 v145, 0xffff0000, v116
	v_lshlrev_b32_e32 v146, 16, v117
	v_and_b32_e32 v147, 0xffff0000, v117
	v_lshlrev_b32_e32 v148, 16, v118
	v_and_b32_e32 v149, 0xffff0000, v118
	v_lshlrev_b32_e32 v150, 16, v119
	v_and_b32_e32 v151, 0xffff0000, v119
	v_pk_fma_f32 v[136:137], v[64:65], s[44:45], v[136:137]
	v_pk_fma_f32 v[138:139], v[66:67], s[44:45], v[138:139]
	v_pk_fma_f32 v[140:141], v[68:69], s[44:45], v[140:141]
	v_pk_fma_f32 v[142:143], v[70:71], s[44:45], v[142:143]
	v_pk_fma_f32 v[144:145], v[72:73], s[44:45], v[144:145]
	v_pk_fma_f32 v[146:147], v[74:75], s[44:45], v[146:147]
	v_pk_fma_f32 v[148:149], v[76:77], s[44:45], v[148:149]
	v_pk_fma_f32 v[150:151], v[78:79], s[44:45], v[150:151]
	v_pk_add_f32 v[152:153], v[136:137], v[138:139]
	v_pk_add_f32 v[152:153], v[152:153], v[140:141]
	v_pk_add_f32 v[152:153], v[152:153], v[142:143]
	v_pk_add_f32 v[152:153], v[152:153], v[144:145]
	v_pk_add_f32 v[152:153], v[152:153], v[146:147]
	v_pk_add_f32 v[152:153], v[152:153], v[148:149]
	v_pk_add_f32 v[152:153], v[152:153], v[150:151]
	v_add_f32_e32 v170, v152, v153
	s_nop 1
	v_add_f32_dpp v168, v170, v170 quad_perm:[1,0,3,2] row_mask:0xf bank_mask:0xf
	s_nop 1
	v_add_f32_dpp v168, v168, v168 quad_perm:[2,3,0,1] row_mask:0xf bank_mask:0xf
	s_nop 1
	v_add_f32_dpp v168, v168, v168 row_half_mirror row_mask:0xf bank_mask:0xf
	s_nop 1
	v_add_f32_dpp v168, v168, v168 row_mirror row_mask:0xf bank_mask:0xf
	s_nop 1
	v_add_f32_dpp v168, v168, v168 row_bcast:15 row_mask:0xa bank_mask:0xf
	s_nop 1
	v_add_f32_dpp v168, v168, v168 row_bcast:31 row_mask:0xc bank_mask:0xf
	s_nop 1
	v_readlane_b32 s42, v168, 63
	s_nop 3
	s_mov_b32 s43, s42
	v_pk_fma_f32 v[136:137], s[42:43], v[172:173], v[136:137]
	v_pk_fma_f32 v[138:139], s[42:43], v[172:173], v[138:139]
	v_pk_fma_f32 v[140:141], s[42:43], v[172:173], v[140:141]
	v_pk_fma_f32 v[142:143], s[42:43], v[172:173], v[142:143]
	v_pk_fma_f32 v[144:145], s[42:43], v[172:173], v[144:145]
	v_pk_fma_f32 v[146:147], s[42:43], v[172:173], v[146:147]
	v_pk_fma_f32 v[148:149], s[42:43], v[172:173], v[148:149]
	v_pk_fma_f32 v[150:151], s[42:43], v[172:173], v[150:151]
	v_pk_mul_f32 v[152:153], v[136:137], v[136:137]
	v_pk_fma_f32 v[152:153], v[138:139], v[138:139], v[152:153]
	v_pk_fma_f32 v[152:153], v[140:141], v[140:141], v[152:153]
	v_pk_fma_f32 v[152:153], v[142:143], v[142:143], v[152:153]
	v_pk_fma_f32 v[152:153], v[144:145], v[144:145], v[152:153]
	v_pk_fma_f32 v[152:153], v[146:147], v[146:147], v[152:153]
	v_pk_fma_f32 v[152:153], v[148:149], v[148:149], v[152:153]
	v_pk_fma_f32 v[152:153], v[150:151], v[150:151], v[152:153]
	v_add_f32_e32 v170, v152, v153
	s_nop 1
	v_add_f32_dpp v168, v170, v170 quad_perm:[1,0,3,2] row_mask:0xf bank_mask:0xf
	s_nop 1
	v_add_f32_dpp v168, v168, v168 quad_perm:[2,3,0,1] row_mask:0xf bank_mask:0xf
	s_nop 1
	v_add_f32_dpp v168, v168, v168 row_half_mirror row_mask:0xf bank_mask:0xf
	s_nop 1
	v_add_f32_dpp v168, v168, v168 row_mirror row_mask:0xf bank_mask:0xf
	s_nop 1
	v_add_f32_dpp v168, v168, v168 row_bcast:15 row_mask:0xa bank_mask:0xf
	s_nop 1
	v_add_f32_dpp v168, v168, v168 row_bcast:31 row_mask:0xc bank_mask:0xf
	s_nop 1
	v_readlane_b32 s42, v168, 63
	s_nop 3
	v_fma_f32 v174, s42, v178, v179
	v_rsq_f32_e32 v174, v174
	s_nop 0
	v_pk_mul_f32 v[136:137], v[136:137], v[174:175] op_sel_hi:[1,0]
	v_pk_mul_f32 v[138:139], v[138:139], v[174:175] op_sel_hi:[1,0]
	v_pk_mul_f32 v[140:141], v[140:141], v[174:175] op_sel_hi:[1,0]
	v_pk_mul_f32 v[142:143], v[142:143], v[174:175] op_sel_hi:[1,0]
	v_pk_mul_f32 v[144:145], v[144:145], v[174:175] op_sel_hi:[1,0]
	v_pk_mul_f32 v[146:147], v[146:147], v[174:175] op_sel_hi:[1,0]
	v_pk_mul_f32 v[148:149], v[148:149], v[174:175] op_sel_hi:[1,0]
	v_pk_mul_f32 v[150:151], v[150:151], v[174:175] op_sel_hi:[1,0]
	v_pk_fma_f32 v[136:137], v[136:137], v[0:1], v[16:17]
	v_pk_fma_f32 v[138:139], v[138:139], v[2:3], v[18:19]
	v_pk_fma_f32 v[140:141], v[140:141], v[4:5], v[20:21]
	v_pk_fma_f32 v[142:143], v[142:143], v[6:7], v[22:23]
	v_pk_fma_f32 v[144:145], v[144:145], v[8:9], v[24:25]
	v_pk_fma_f32 v[146:147], v[146:147], v[10:11], v[26:27]
	v_pk_fma_f32 v[148:149], v[148:149], v[12:13], v[28:29]
	v_pk_fma_f32 v[150:151], v[150:151], v[14:15], v[30:31]
	global_store_dwordx4 v176, v[136:139], s[8:9] offset:0
	global_store_dwordx4 v176, v[140:143], s[8:9] offset:1024
	global_store_dwordx4 v176, v[144:147], s[8:9] offset:2048
	global_store_dwordx4 v176, v[148:151], s[8:9] offset:3072
	s_add_u32 s8, s8, 0x1000
	s_addc_u32 s9, s9, 0
	s_add_u32 s12, s12, 0x800
	s_addc_u32 s13, s13, 0
	global_load_dwordx4 v[64:67], v176, s[14:15] offset:0
	global_load_dwordx4 v[68:71], v176, s[14:15] offset:1024
	global_load_dwordx4 v[72:75], v176, s[14:15] offset:2048
	global_load_dwordx4 v[76:79], v176, s[14:15] offset:3072
	global_load_dwordx2 v[112:113], v177, s[6:7] offset:0
	global_load_dwordx2 v[114:115], v177, s[6:7] offset:512
	global_load_dwordx2 v[116:117], v177, s[6:7] offset:1024
	global_load_dwordx2 v[118:119], v177, s[6:7] offset:1536
	s_add_u32 s14, s14, 0x1000
	s_addc_u32 s15, s15, 0
	s_add_u32 s6, s6, 0x800
	s_addc_u32 s7, s7, 0
	s_waitcnt vmcnt(24)
	v_lshlrev_b32_e32 v136, 16, v120
	v_and_b32_e32 v137, 0xffff0000, v120
	v_lshlrev_b32_e32 v138, 16, v121
	v_and_b32_e32 v139, 0xffff0000, v121
	v_lshlrev_b32_e32 v140, 16, v122
	v_and_b32_e32 v141, 0xffff0000, v122
	v_lshlrev_b32_e32 v142, 16, v123
	v_and_b32_e32 v143, 0xffff0000, v123
	v_lshlrev_b32_e32 v144, 16, v124
	v_and_b32_e32 v145, 0xffff0000, v124
	v_lshlrev_b32_e32 v146, 16, v125
	v_and_b32_e32 v147, 0xffff0000, v125
	v_lshlrev_b32_e32 v148, 16, v126
	v_and_b32_e32 v149, 0xffff0000, v126
	v_lshlrev_b32_e32 v150, 16, v127
	v_and_b32_e32 v151, 0xffff0000, v127
	v_pk_fma_f32 v[136:137], v[80:81], s[44:45], v[136:137]
	v_pk_fma_f32 v[138:139], v[82:83], s[44:45], v[138:139]
	v_pk_fma_f32 v[140:141], v[84:85], s[44:45], v[140:141]
	v_pk_fma_f32 v[142:143], v[86:87], s[44:45], v[142:143]
	v_pk_fma_f32 v[144:145], v[88:89], s[44:45], v[144:145]
	v_pk_fma_f32 v[146:147], v[90:91], s[44:45], v[146:147]
	v_pk_fma_f32 v[148:149], v[92:93], s[44:45], v[148:149]
	v_pk_fma_f32 v[150:151], v[94:95], s[44:45], v[150:151]
	v_pk_add_f32 v[152:153], v[136:137], v[138:139]
	v_pk_add_f32 v[152:153], v[152:153], v[140:141]
	v_pk_add_f32 v[152:153], v[152:153], v[142:143]
	v_pk_add_f32 v[152:153], v[152:153], v[144:145]
	v_pk_add_f32 v[152:153], v[152:153], v[146:147]
	v_pk_add_f32 v[152:153], v[152:153], v[148:149]
	v_pk_add_f32 v[152:153], v[152:153], v[150:151]
	v_add_f32_e32 v170, v152, v153
	s_nop 1
	v_add_f32_dpp v168, v170, v170 quad_perm:[1,0,3,2] row_mask:0xf bank_mask:0xf
	s_nop 1
	v_add_f32_dpp v168, v168, v168 quad_perm:[2,3,0,1] row_mask:0xf bank_mask:0xf
	s_nop 1
	v_add_f32_dpp v168, v168, v168 row_half_mirror row_mask:0xf bank_mask:0xf
	s_nop 1
	v_add_f32_dpp v168, v168, v168 row_mirror row_mask:0xf bank_mask:0xf
	s_nop 1
	v_add_f32_dpp v168, v168, v168 row_bcast:15 row_mask:0xa bank_mask:0xf
	s_nop 1
	v_add_f32_dpp v168, v168, v168 row_bcast:31 row_mask:0xc bank_mask:0xf
	s_nop 1
	v_readlane_b32 s42, v168, 63
	s_nop 3
	s_mov_b32 s43, s42
	v_pk_fma_f32 v[136:137], s[42:43], v[172:173], v[136:137]
	v_pk_fma_f32 v[138:139], s[42:43], v[172:173], v[138:139]
	v_pk_fma_f32 v[140:141], s[42:43], v[172:173], v[140:141]
	v_pk_fma_f32 v[142:143], s[42:43], v[172:173], v[142:143]
	v_pk_fma_f32 v[144:145], s[42:43], v[172:173], v[144:145]
	v_pk_fma_f32 v[146:147], s[42:43], v[172:173], v[146:147]
	v_pk_fma_f32 v[148:149], s[42:43], v[172:173], v[148:149]
	v_pk_fma_f32 v[150:151], s[42:43], v[172:173], v[150:151]
	v_pk_mul_f32 v[152:153], v[136:137], v[136:137]
	v_pk_fma_f32 v[152:153], v[138:139], v[138:139], v[152:153]
	v_pk_fma_f32 v[152:153], v[140:141], v[140:141], v[152:153]
	v_pk_fma_f32 v[152:153], v[142:143], v[142:143], v[152:153]
	v_pk_fma_f32 v[152:153], v[144:145], v[144:145], v[152:153]
	v_pk_fma_f32 v[152:153], v[146:147], v[146:147], v[152:153]
	v_pk_fma_f32 v[152:153], v[148:149], v[148:149], v[152:153]
	v_pk_fma_f32 v[152:153], v[150:151], v[150:151], v[152:153]
	v_add_f32_e32 v170, v152, v153
	s_nop 1
	v_add_f32_dpp v168, v170, v170 quad_perm:[1,0,3,2] row_mask:0xf bank_mask:0xf
	s_nop 1
	v_add_f32_dpp v168, v168, v168 quad_perm:[2,3,0,1] row_mask:0xf bank_mask:0xf
	s_nop 1
	v_add_f32_dpp v168, v168, v168 row_half_mirror row_mask:0xf bank_mask:0xf
	s_nop 1
	v_add_f32_dpp v168, v168, v168 row_mirror row_mask:0xf bank_mask:0xf
	s_nop 1
	v_add_f32_dpp v168, v168, v168 row_bcast:15 row_mask:0xa bank_mask:0xf
	s_nop 1
	v_add_f32_dpp v168, v168, v168 row_bcast:31 row_mask:0xc bank_mask:0xf
	s_nop 1
	v_readlane_b32 s42, v168, 63
	s_nop 3
	v_fma_f32 v174, s42, v178, v179
	v_rsq_f32_e32 v174, v174
	s_nop 0
	v_pk_mul_f32 v[136:137], v[136:137], v[174:175] op_sel_hi:[1,0]
	v_pk_mul_f32 v[138:139], v[138:139], v[174:175] op_sel_hi:[1,0]
	v_pk_mul_f32 v[140:141], v[140:141], v[174:175] op_sel_hi:[1,0]
	v_pk_mul_f32 v[142:143], v[142:143], v[174:175] op_sel_hi:[1,0]
	v_pk_mul_f32 v[144:145], v[144:145], v[174:175] op_sel_hi:[1,0]
	v_pk_mul_f32 v[146:147], v[146:147], v[174:175] op_sel_hi:[1,0]
	v_pk_mul_f32 v[148:149], v[148:149], v[174:175] op_sel_hi:[1,0]
	v_pk_mul_f32 v[150:151], v[150:151], v[174:175] op_sel_hi:[1,0]
	v_pk_fma_f32 v[136:137], v[136:137], v[0:1], v[16:17]
	v_pk_fma_f32 v[138:139], v[138:139], v[2:3], v[18:19]
	v_pk_fma_f32 v[140:141], v[140:141], v[4:5], v[20:21]
	v_pk_fma_f32 v[142:143], v[142:143], v[6:7], v[22:23]
	v_pk_fma_f32 v[144:145], v[144:145], v[8:9], v[24:25]
	v_pk_fma_f32 v[146:147], v[146:147], v[10:11], v[26:27]
	v_pk_fma_f32 v[148:149], v[148:149], v[12:13], v[28:29]
	v_pk_fma_f32 v[150:151], v[150:151], v[14:15], v[30:31]
	global_store_dwordx4 v176, v[136:139], s[8:9] offset:0
	global_store_dwordx4 v176, v[140:143], s[8:9] offset:1024
	global_store_dwordx4 v176, v[144:147], s[8:9] offset:2048
	global_store_dwordx4 v176, v[148:151], s[8:9] offset:3072
	s_add_u32 s8, s8, 0x1000
	s_addc_u32 s9, s9, 0
	s_add_u32 s12, s12, 0x800
	s_addc_u32 s13, s13, 0
	global_load_dwordx4 v[80:83], v176, s[14:15] offset:0
	global_load_dwordx4 v[84:87], v176, s[14:15] offset:1024
	global_load_dwordx4 v[88:91], v176, s[14:15] offset:2048
	global_load_dwordx4 v[92:95], v176, s[14:15] offset:3072
	global_load_dwordx2 v[120:121], v177, s[6:7] offset:0
	global_load_dwordx2 v[122:123], v177, s[6:7] offset:512
	global_load_dwordx2 v[124:125], v177, s[6:7] offset:1024
	global_load_dwordx2 v[126:127], v177, s[6:7] offset:1536
	s_add_u32 s14, s14, 0x1000
	s_addc_u32 s15, s15, 0
	s_add_u32 s6, s6, 0x800
	s_addc_u32 s7, s7, 0
	s_waitcnt vmcnt(24)
	v_lshlrev_b32_e32 v136, 16, v128
	v_and_b32_e32 v137, 0xffff0000, v128
	v_lshlrev_b32_e32 v138, 16, v129
	v_and_b32_e32 v139, 0xffff0000, v129
	v_lshlrev_b32_e32 v140, 16, v130
	v_and_b32_e32 v141, 0xffff0000, v130
	v_lshlrev_b32_e32 v142, 16, v131
	v_and_b32_e32 v143, 0xffff0000, v131
	v_lshlrev_b32_e32 v144, 16, v132
	v_and_b32_e32 v145, 0xffff0000, v132
	v_lshlrev_b32_e32 v146, 16, v133
	v_and_b32_e32 v147, 0xffff0000, v133
	v_lshlrev_b32_e32 v148, 16, v134
	v_and_b32_e32 v149, 0xffff0000, v134
	v_lshlrev_b32_e32 v150, 16, v135
	v_and_b32_e32 v151, 0xffff0000, v135
	v_pk_fma_f32 v[136:137], v[96:97], s[44:45], v[136:137]
	v_pk_fma_f32 v[138:139], v[98:99], s[44:45], v[138:139]
	v_pk_fma_f32 v[140:141], v[100:101], s[44:45], v[140:141]
	v_pk_fma_f32 v[142:143], v[102:103], s[44:45], v[142:143]
	v_pk_fma_f32 v[144:145], v[104:105], s[44:45], v[144:145]
	v_pk_fma_f32 v[146:147], v[106:107], s[44:45], v[146:147]
	v_pk_fma_f32 v[148:149], v[108:109], s[44:45], v[148:149]
	v_pk_fma_f32 v[150:151], v[110:111], s[44:45], v[150:151]
	v_pk_add_f32 v[152:153], v[136:137], v[138:139]
	v_pk_add_f32 v[152:153], v[152:153], v[140:141]
	v_pk_add_f32 v[152:153], v[152:153], v[142:143]
	v_pk_add_f32 v[152:153], v[152:153], v[144:145]
	v_pk_add_f32 v[152:153], v[152:153], v[146:147]
	v_pk_add_f32 v[152:153], v[152:153], v[148:149]
	v_pk_add_f32 v[152:153], v[152:153], v[150:151]
	v_add_f32_e32 v170, v152, v153
	s_nop 1
	v_add_f32_dpp v168, v170, v170 quad_perm:[1,0,3,2] row_mask:0xf bank_mask:0xf
	s_nop 1
	v_add_f32_dpp v168, v168, v168 quad_perm:[2,3,0,1] row_mask:0xf bank_mask:0xf
	s_nop 1
	v_add_f32_dpp v168, v168, v168 row_half_mirror row_mask:0xf bank_mask:0xf
	s_nop 1
	v_add_f32_dpp v168, v168, v168 row_mirror row_mask:0xf bank_mask:0xf
	s_nop 1
	v_add_f32_dpp v168, v168, v168 row_bcast:15 row_mask:0xa bank_mask:0xf
	s_nop 1
	v_add_f32_dpp v168, v168, v168 row_bcast:31 row_mask:0xc bank_mask:0xf
	s_nop 1
	v_readlane_b32 s42, v168, 63
	s_nop 3
	s_mov_b32 s43, s42
	v_pk_fma_f32 v[136:137], s[42:43], v[172:173], v[136:137]
	v_pk_fma_f32 v[138:139], s[42:43], v[172:173], v[138:139]
	v_pk_fma_f32 v[140:141], s[42:43], v[172:173], v[140:141]
	v_pk_fma_f32 v[142:143], s[42:43], v[172:173], v[142:143]
	v_pk_fma_f32 v[144:145], s[42:43], v[172:173], v[144:145]
	v_pk_fma_f32 v[146:147], s[42:43], v[172:173], v[146:147]
	v_pk_fma_f32 v[148:149], s[42:43], v[172:173], v[148:149]
	v_pk_fma_f32 v[150:151], s[42:43], v[172:173], v[150:151]
	v_pk_mul_f32 v[152:153], v[136:137], v[136:137]
	v_pk_fma_f32 v[152:153], v[138:139], v[138:139], v[152:153]
	v_pk_fma_f32 v[152:153], v[140:141], v[140:141], v[152:153]
	v_pk_fma_f32 v[152:153], v[142:143], v[142:143], v[152:153]
	v_pk_fma_f32 v[152:153], v[144:145], v[144:145], v[152:153]
	v_pk_fma_f32 v[152:153], v[146:147], v[146:147], v[152:153]
	v_pk_fma_f32 v[152:153], v[148:149], v[148:149], v[152:153]
	v_pk_fma_f32 v[152:153], v[150:151], v[150:151], v[152:153]
	v_add_f32_e32 v170, v152, v153
	s_nop 1
	v_add_f32_dpp v168, v170, v170 quad_perm:[1,0,3,2] row_mask:0xf bank_mask:0xf
	s_nop 1
	v_add_f32_dpp v168, v168, v168 quad_perm:[2,3,0,1] row_mask:0xf bank_mask:0xf
	s_nop 1
	v_add_f32_dpp v168, v168, v168 row_half_mirror row_mask:0xf bank_mask:0xf
	s_nop 1
	v_add_f32_dpp v168, v168, v168 row_mirror row_mask:0xf bank_mask:0xf
	s_nop 1
	v_add_f32_dpp v168, v168, v168 row_bcast:15 row_mask:0xa bank_mask:0xf
	s_nop 1
	v_add_f32_dpp v168, v168, v168 row_bcast:31 row_mask:0xc bank_mask:0xf
	s_nop 1
	v_readlane_b32 s42, v168, 63
	s_nop 3
	v_fma_f32 v174, s42, v178, v179
	v_rsq_f32_e32 v174, v174
	s_nop 0
	v_pk_mul_f32 v[136:137], v[136:137], v[174:175] op_sel_hi:[1,0]
	v_pk_mul_f32 v[138:139], v[138:139], v[174:175] op_sel_hi:[1,0]
	v_pk_mul_f32 v[140:141], v[140:141], v[174:175] op_sel_hi:[1,0]
	v_pk_mul_f32 v[142:143], v[142:143], v[174:175] op_sel_hi:[1,0]
	v_pk_mul_f32 v[144:145], v[144:145], v[174:175] op_sel_hi:[1,0]
	v_pk_mul_f32 v[146:147], v[146:147], v[174:175] op_sel_hi:[1,0]
	v_pk_mul_f32 v[148:149], v[148:149], v[174:175] op_sel_hi:[1,0]
	v_pk_mul_f32 v[150:151], v[150:151], v[174:175] op_sel_hi:[1,0]
	v_pk_fma_f32 v[136:137], v[136:137], v[0:1], v[16:17]
	v_pk_fma_f32 v[138:139], v[138:139], v[2:3], v[18:19]
	v_pk_fma_f32 v[140:141], v[140:141], v[4:5], v[20:21]
	v_pk_fma_f32 v[142:143], v[142:143], v[6:7], v[22:23]
	v_pk_fma_f32 v[144:145], v[144:145], v[8:9], v[24:25]
	v_pk_fma_f32 v[146:147], v[146:147], v[10:11], v[26:27]
	v_pk_fma_f32 v[148:149], v[148:149], v[12:13], v[28:29]
	v_pk_fma_f32 v[150:151], v[150:151], v[14:15], v[30:31]
	global_store_dwordx4 v176, v[136:139], s[8:9] offset:0
	global_store_dwordx4 v176, v[140:143], s[8:9] offset:1024
	global_store_dwordx4 v176, v[144:147], s[8:9] offset:2048
	global_store_dwordx4 v176, v[148:151], s[8:9] offset:3072
	s_add_u32 s8, s8, 0x1000
	s_addc_u32 s9, s9, 0
	s_add_u32 s12, s12, 0x800
	s_addc_u32 s13, s13, 0
	global_load_dwordx4 v[96:99], v176, s[14:15] offset:0
	global_load_dwordx4 v[100:103], v176, s[14:15] offset:1024
	global_load_dwordx4 v[104:107], v176, s[14:15] offset:2048
	global_load_dwordx4 v[108:111], v176, s[14:15] offset:3072
	global_load_dwordx2 v[128:129], v177, s[6:7] offset:0
	global_load_dwordx2 v[130:131], v177, s[6:7] offset:512
	global_load_dwordx2 v[132:133], v177, s[6:7] offset:1024
	global_load_dwordx2 v[134:135], v177, s[6:7] offset:1536
	s_add_u32 s14, s14, 0x1000
	s_addc_u32 s15, s15, 0
	s_add_u32 s6, s6, 0x800
	s_addc_u32 s7, s7, 0
	s_waitcnt vmcnt(24)
	v_lshlrev_b32_e32 v136, 16, v112
	v_and_b32_e32 v137, 0xffff0000, v112
	v_lshlrev_b32_e32 v138, 16, v113
	v_and_b32_e32 v139, 0xffff0000, v113
	v_lshlrev_b32_e32 v140, 16, v114
	v_and_b32_e32 v141, 0xffff0000, v114
	v_lshlrev_b32_e32 v142, 16, v115
	v_and_b32_e32 v143, 0xffff0000, v115
	v_lshlrev_b32_e32 v144, 16, v116
	v_and_b32_e32 v145, 0xffff0000, v116
	v_lshlrev_b32_e32 v146, 16, v117
	v_and_b32_e32 v147, 0xffff0000, v117
	v_lshlrev_b32_e32 v148, 16, v118
	v_and_b32_e32 v149, 0xffff0000, v118
	v_lshlrev_b32_e32 v150, 16, v119
	v_and_b32_e32 v151, 0xffff0000, v119
	v_pk_fma_f32 v[136:137], v[64:65], s[44:45], v[136:137]
	v_pk_fma_f32 v[138:139], v[66:67], s[44:45], v[138:139]
	v_pk_fma_f32 v[140:141], v[68:69], s[44:45], v[140:141]
	v_pk_fma_f32 v[142:143], v[70:71], s[44:45], v[142:143]
	v_pk_fma_f32 v[144:145], v[72:73], s[44:45], v[144:145]
	v_pk_fma_f32 v[146:147], v[74:75], s[44:45], v[146:147]
	v_pk_fma_f32 v[148:149], v[76:77], s[44:45], v[148:149]
	v_pk_fma_f32 v[150:151], v[78:79], s[44:45], v[150:151]
	v_pk_add_f32 v[152:153], v[136:137], v[138:139]
	v_pk_add_f32 v[152:153], v[152:153], v[140:141]
	v_pk_add_f32 v[152:153], v[152:153], v[142:143]
	v_pk_add_f32 v[152:153], v[152:153], v[144:145]
	v_pk_add_f32 v[152:153], v[152:153], v[146:147]
	v_pk_add_f32 v[152:153], v[152:153], v[148:149]
	v_pk_add_f32 v[152:153], v[152:153], v[150:151]
	v_add_f32_e32 v170, v152, v153
	s_nop 1
	v_add_f32_dpp v168, v170, v170 quad_perm:[1,0,3,2] row_mask:0xf bank_mask:0xf
	s_nop 1
	v_add_f32_dpp v168, v168, v168 quad_perm:[2,3,0,1] row_mask:0xf bank_mask:0xf
	s_nop 1
	v_add_f32_dpp v168, v168, v168 row_half_mirror row_mask:0xf bank_mask:0xf
	s_nop 1
	v_add_f32_dpp v168, v168, v168 row_mirror row_mask:0xf bank_mask:0xf
	s_nop 1
	v_add_f32_dpp v168, v168, v168 row_bcast:15 row_mask:0xa bank_mask:0xf
	s_nop 1
	v_add_f32_dpp v168, v168, v168 row_bcast:31 row_mask:0xc bank_mask:0xf
	s_nop 1
	v_readlane_b32 s42, v168, 63
	s_nop 3
	s_mov_b32 s43, s42
	v_pk_fma_f32 v[136:137], s[42:43], v[172:173], v[136:137]
	v_pk_fma_f32 v[138:139], s[42:43], v[172:173], v[138:139]
	v_pk_fma_f32 v[140:141], s[42:43], v[172:173], v[140:141]
	v_pk_fma_f32 v[142:143], s[42:43], v[172:173], v[142:143]
	v_pk_fma_f32 v[144:145], s[42:43], v[172:173], v[144:145]
	v_pk_fma_f32 v[146:147], s[42:43], v[172:173], v[146:147]
	v_pk_fma_f32 v[148:149], s[42:43], v[172:173], v[148:149]
	v_pk_fma_f32 v[150:151], s[42:43], v[172:173], v[150:151]
	v_pk_mul_f32 v[152:153], v[136:137], v[136:137]
	v_pk_fma_f32 v[152:153], v[138:139], v[138:139], v[152:153]
	v_pk_fma_f32 v[152:153], v[140:141], v[140:141], v[152:153]
	v_pk_fma_f32 v[152:153], v[142:143], v[142:143], v[152:153]
	v_pk_fma_f32 v[152:153], v[144:145], v[144:145], v[152:153]
	v_pk_fma_f32 v[152:153], v[146:147], v[146:147], v[152:153]
	v_pk_fma_f32 v[152:153], v[148:149], v[148:149], v[152:153]
	v_pk_fma_f32 v[152:153], v[150:151], v[150:151], v[152:153]
	v_add_f32_e32 v170, v152, v153
	s_nop 1
	v_add_f32_dpp v168, v170, v170 quad_perm:[1,0,3,2] row_mask:0xf bank_mask:0xf
	s_nop 1
	v_add_f32_dpp v168, v168, v168 quad_perm:[2,3,0,1] row_mask:0xf bank_mask:0xf
	s_nop 1
	v_add_f32_dpp v168, v168, v168 row_half_mirror row_mask:0xf bank_mask:0xf
	s_nop 1
	v_add_f32_dpp v168, v168, v168 row_mirror row_mask:0xf bank_mask:0xf
	s_nop 1
	v_add_f32_dpp v168, v168, v168 row_bcast:15 row_mask:0xa bank_mask:0xf
	s_nop 1
	v_add_f32_dpp v168, v168, v168 row_bcast:31 row_mask:0xc bank_mask:0xf
	s_nop 1
	v_readlane_b32 s42, v168, 63
	s_nop 3
	v_fma_f32 v174, s42, v178, v179
	v_rsq_f32_e32 v174, v174
	s_nop 0
	v_pk_mul_f32 v[136:137], v[136:137], v[174:175] op_sel_hi:[1,0]
	v_pk_mul_f32 v[138:139], v[138:139], v[174:175] op_sel_hi:[1,0]
	v_pk_mul_f32 v[140:141], v[140:141], v[174:175] op_sel_hi:[1,0]
	v_pk_mul_f32 v[142:143], v[142:143], v[174:175] op_sel_hi:[1,0]
	v_pk_mul_f32 v[144:145], v[144:145], v[174:175] op_sel_hi:[1,0]
	v_pk_mul_f32 v[146:147], v[146:147], v[174:175] op_sel_hi:[1,0]
	v_pk_mul_f32 v[148:149], v[148:149], v[174:175] op_sel_hi:[1,0]
	v_pk_mul_f32 v[150:151], v[150:151], v[174:175] op_sel_hi:[1,0]
	v_pk_fma_f32 v[136:137], v[136:137], v[0:1], v[16:17]
	v_pk_fma_f32 v[138:139], v[138:139], v[2:3], v[18:19]
	v_pk_fma_f32 v[140:141], v[140:141], v[4:5], v[20:21]
	v_pk_fma_f32 v[142:143], v[142:143], v[6:7], v[22:23]
	v_pk_fma_f32 v[144:145], v[144:145], v[8:9], v[24:25]
	v_pk_fma_f32 v[146:147], v[146:147], v[10:11], v[26:27]
	v_pk_fma_f32 v[148:149], v[148:149], v[12:13], v[28:29]
	v_pk_fma_f32 v[150:151], v[150:151], v[14:15], v[30:31]
	global_store_dwordx4 v176, v[136:139], s[8:9] offset:0
	global_store_dwordx4 v176, v[140:143], s[8:9] offset:1024
	global_store_dwordx4 v176, v[144:147], s[8:9] offset:2048
	global_store_dwordx4 v176, v[148:151], s[8:9] offset:3072
	s_add_u32 s8, s8, 0x1000
	s_addc_u32 s9, s9, 0
	s_add_u32 s12, s12, 0x800
	s_addc_u32 s13, s13, 0
	global_load_dwordx4 v[64:67], v176, s[14:15] offset:0
	global_load_dwordx4 v[68:71], v176, s[14:15] offset:1024
	global_load_dwordx4 v[72:75], v176, s[14:15] offset:2048
	global_load_dwordx4 v[76:79], v176, s[14:15] offset:3072
	global_load_dwordx2 v[112:113], v177, s[6:7] offset:0
	global_load_dwordx2 v[114:115], v177, s[6:7] offset:512
	global_load_dwordx2 v[116:117], v177, s[6:7] offset:1024
	global_load_dwordx2 v[118:119], v177, s[6:7] offset:1536
	s_add_u32 s14, s14, 0x1000
	s_addc_u32 s15, s15, 0
	s_add_u32 s6, s6, 0x800
	s_addc_u32 s7, s7, 0
	s_waitcnt vmcnt(24)
	v_lshlrev_b32_e32 v136, 16, v120
	v_and_b32_e32 v137, 0xffff0000, v120
	v_lshlrev_b32_e32 v138, 16, v121
	v_and_b32_e32 v139, 0xffff0000, v121
	v_lshlrev_b32_e32 v140, 16, v122
	v_and_b32_e32 v141, 0xffff0000, v122
	v_lshlrev_b32_e32 v142, 16, v123
	v_and_b32_e32 v143, 0xffff0000, v123
	v_lshlrev_b32_e32 v144, 16, v124
	v_and_b32_e32 v145, 0xffff0000, v124
	v_lshlrev_b32_e32 v146, 16, v125
	v_and_b32_e32 v147, 0xffff0000, v125
	v_lshlrev_b32_e32 v148, 16, v126
	v_and_b32_e32 v149, 0xffff0000, v126
	v_lshlrev_b32_e32 v150, 16, v127
	v_and_b32_e32 v151, 0xffff0000, v127
	v_pk_fma_f32 v[136:137], v[80:81], s[44:45], v[136:137]
	v_pk_fma_f32 v[138:139], v[82:83], s[44:45], v[138:139]
	v_pk_fma_f32 v[140:141], v[84:85], s[44:45], v[140:141]
	v_pk_fma_f32 v[142:143], v[86:87], s[44:45], v[142:143]
	v_pk_fma_f32 v[144:145], v[88:89], s[44:45], v[144:145]
	v_pk_fma_f32 v[146:147], v[90:91], s[44:45], v[146:147]
	v_pk_fma_f32 v[148:149], v[92:93], s[44:45], v[148:149]
	v_pk_fma_f32 v[150:151], v[94:95], s[44:45], v[150:151]
	v_pk_add_f32 v[152:153], v[136:137], v[138:139]
	v_pk_add_f32 v[152:153], v[152:153], v[140:141]
	v_pk_add_f32 v[152:153], v[152:153], v[142:143]
	v_pk_add_f32 v[152:153], v[152:153], v[144:145]
	v_pk_add_f32 v[152:153], v[152:153], v[146:147]
	v_pk_add_f32 v[152:153], v[152:153], v[148:149]
	v_pk_add_f32 v[152:153], v[152:153], v[150:151]
	v_add_f32_e32 v170, v152, v153
	s_nop 1
	v_add_f32_dpp v168, v170, v170 quad_perm:[1,0,3,2] row_mask:0xf bank_mask:0xf
	s_nop 1
	v_add_f32_dpp v168, v168, v168 quad_perm:[2,3,0,1] row_mask:0xf bank_mask:0xf
	s_nop 1
	v_add_f32_dpp v168, v168, v168 row_half_mirror row_mask:0xf bank_mask:0xf
	s_nop 1
	v_add_f32_dpp v168, v168, v168 row_mirror row_mask:0xf bank_mask:0xf
	s_nop 1
	v_add_f32_dpp v168, v168, v168 row_bcast:15 row_mask:0xa bank_mask:0xf
	s_nop 1
	v_add_f32_dpp v168, v168, v168 row_bcast:31 row_mask:0xc bank_mask:0xf
	s_nop 1
	v_readlane_b32 s42, v168, 63
	s_nop 3
	s_mov_b32 s43, s42
	v_pk_fma_f32 v[136:137], s[42:43], v[172:173], v[136:137]
	v_pk_fma_f32 v[138:139], s[42:43], v[172:173], v[138:139]
	v_pk_fma_f32 v[140:141], s[42:43], v[172:173], v[140:141]
	v_pk_fma_f32 v[142:143], s[42:43], v[172:173], v[142:143]
	v_pk_fma_f32 v[144:145], s[42:43], v[172:173], v[144:145]
	v_pk_fma_f32 v[146:147], s[42:43], v[172:173], v[146:147]
	v_pk_fma_f32 v[148:149], s[42:43], v[172:173], v[148:149]
	v_pk_fma_f32 v[150:151], s[42:43], v[172:173], v[150:151]
	v_pk_mul_f32 v[152:153], v[136:137], v[136:137]
	v_pk_fma_f32 v[152:153], v[138:139], v[138:139], v[152:153]
	v_pk_fma_f32 v[152:153], v[140:141], v[140:141], v[152:153]
	v_pk_fma_f32 v[152:153], v[142:143], v[142:143], v[152:153]
	v_pk_fma_f32 v[152:153], v[144:145], v[144:145], v[152:153]
	v_pk_fma_f32 v[152:153], v[146:147], v[146:147], v[152:153]
	v_pk_fma_f32 v[152:153], v[148:149], v[148:149], v[152:153]
	v_pk_fma_f32 v[152:153], v[150:151], v[150:151], v[152:153]
	v_add_f32_e32 v170, v152, v153
	s_nop 1
	v_add_f32_dpp v168, v170, v170 quad_perm:[1,0,3,2] row_mask:0xf bank_mask:0xf
	s_nop 1
	v_add_f32_dpp v168, v168, v168 quad_perm:[2,3,0,1] row_mask:0xf bank_mask:0xf
	s_nop 1
	v_add_f32_dpp v168, v168, v168 row_half_mirror row_mask:0xf bank_mask:0xf
	s_nop 1
	v_add_f32_dpp v168, v168, v168 row_mirror row_mask:0xf bank_mask:0xf
	s_nop 1
	v_add_f32_dpp v168, v168, v168 row_bcast:15 row_mask:0xa bank_mask:0xf
	s_nop 1
	v_add_f32_dpp v168, v168, v168 row_bcast:31 row_mask:0xc bank_mask:0xf
	s_nop 1
	v_readlane_b32 s42, v168, 63
	s_nop 3
	v_fma_f32 v174, s42, v178, v179
	v_rsq_f32_e32 v174, v174
	s_nop 0
	v_pk_mul_f32 v[136:137], v[136:137], v[174:175] op_sel_hi:[1,0]
	v_pk_mul_f32 v[138:139], v[138:139], v[174:175] op_sel_hi:[1,0]
	v_pk_mul_f32 v[140:141], v[140:141], v[174:175] op_sel_hi:[1,0]
	v_pk_mul_f32 v[142:143], v[142:143], v[174:175] op_sel_hi:[1,0]
	v_pk_mul_f32 v[144:145], v[144:145], v[174:175] op_sel_hi:[1,0]
	v_pk_mul_f32 v[146:147], v[146:147], v[174:175] op_sel_hi:[1,0]
	v_pk_mul_f32 v[148:149], v[148:149], v[174:175] op_sel_hi:[1,0]
	v_pk_mul_f32 v[150:151], v[150:151], v[174:175] op_sel_hi:[1,0]
	v_pk_fma_f32 v[136:137], v[136:137], v[0:1], v[16:17]
	v_pk_fma_f32 v[138:139], v[138:139], v[2:3], v[18:19]
	v_pk_fma_f32 v[140:141], v[140:141], v[4:5], v[20:21]
	v_pk_fma_f32 v[142:143], v[142:143], v[6:7], v[22:23]
	v_pk_fma_f32 v[144:145], v[144:145], v[8:9], v[24:25]
	v_pk_fma_f32 v[146:147], v[146:147], v[10:11], v[26:27]
	v_pk_fma_f32 v[148:149], v[148:149], v[12:13], v[28:29]
	v_pk_fma_f32 v[150:151], v[150:151], v[14:15], v[30:31]
	global_store_dwordx4 v176, v[136:139], s[8:9] offset:0
	global_store_dwordx4 v176, v[140:143], s[8:9] offset:1024
	global_store_dwordx4 v176, v[144:147], s[8:9] offset:2048
	global_store_dwordx4 v176, v[148:151], s[8:9] offset:3072
	s_add_u32 s8, s8, 0x1000
	s_addc_u32 s9, s9, 0
	s_add_u32 s12, s12, 0x800
	s_addc_u32 s13, s13, 0
	s_waitcnt vmcnt(16)
	v_lshlrev_b32_e32 v136, 16, v128
	v_and_b32_e32 v137, 0xffff0000, v128
	v_lshlrev_b32_e32 v138, 16, v129
	v_and_b32_e32 v139, 0xffff0000, v129
	v_lshlrev_b32_e32 v140, 16, v130
	v_and_b32_e32 v141, 0xffff0000, v130
	v_lshlrev_b32_e32 v142, 16, v131
	v_and_b32_e32 v143, 0xffff0000, v131
	v_lshlrev_b32_e32 v144, 16, v132
	v_and_b32_e32 v145, 0xffff0000, v132
	v_lshlrev_b32_e32 v146, 16, v133
	v_and_b32_e32 v147, 0xffff0000, v133
	v_lshlrev_b32_e32 v148, 16, v134
	v_and_b32_e32 v149, 0xffff0000, v134
	v_lshlrev_b32_e32 v150, 16, v135
	v_and_b32_e32 v151, 0xffff0000, v135
	v_pk_fma_f32 v[136:137], v[96:97], s[44:45], v[136:137]
	v_pk_fma_f32 v[138:139], v[98:99], s[44:45], v[138:139]
	v_pk_fma_f32 v[140:141], v[100:101], s[44:45], v[140:141]
	v_pk_fma_f32 v[142:143], v[102:103], s[44:45], v[142:143]
	v_pk_fma_f32 v[144:145], v[104:105], s[44:45], v[144:145]
	v_pk_fma_f32 v[146:147], v[106:107], s[44:45], v[146:147]
	v_pk_fma_f32 v[148:149], v[108:109], s[44:45], v[148:149]
	v_pk_fma_f32 v[150:151], v[110:111], s[44:45], v[150:151]
	v_pk_add_f32 v[152:153], v[136:137], v[138:139]
	v_pk_add_f32 v[152:153], v[152:153], v[140:141]
	v_pk_add_f32 v[152:153], v[152:153], v[142:143]
	v_pk_add_f32 v[152:153], v[152:153], v[144:145]
	v_pk_add_f32 v[152:153], v[152:153], v[146:147]
	v_pk_add_f32 v[152:153], v[152:153], v[148:149]
	v_pk_add_f32 v[152:153], v[152:153], v[150:151]
	v_add_f32_e32 v170, v152, v153
	s_nop 1
	v_add_f32_dpp v168, v170, v170 quad_perm:[1,0,3,2] row_mask:0xf bank_mask:0xf
	s_nop 1
	v_add_f32_dpp v168, v168, v168 quad_perm:[2,3,0,1] row_mask:0xf bank_mask:0xf
	s_nop 1
	v_add_f32_dpp v168, v168, v168 row_half_mirror row_mask:0xf bank_mask:0xf
	s_nop 1
	v_add_f32_dpp v168, v168, v168 row_mirror row_mask:0xf bank_mask:0xf
	s_nop 1
	v_add_f32_dpp v168, v168, v168 row_bcast:15 row_mask:0xa bank_mask:0xf
	s_nop 1
	v_add_f32_dpp v168, v168, v168 row_bcast:31 row_mask:0xc bank_mask:0xf
	s_nop 1
	v_readlane_b32 s42, v168, 63
	s_nop 3
	s_mov_b32 s43, s42
	v_pk_fma_f32 v[136:137], s[42:43], v[172:173], v[136:137]
	v_pk_fma_f32 v[138:139], s[42:43], v[172:173], v[138:139]
	v_pk_fma_f32 v[140:141], s[42:43], v[172:173], v[140:141]
	v_pk_fma_f32 v[142:143], s[42:43], v[172:173], v[142:143]
	v_pk_fma_f32 v[144:145], s[42:43], v[172:173], v[144:145]
	v_pk_fma_f32 v[146:147], s[42:43], v[172:173], v[146:147]
	v_pk_fma_f32 v[148:149], s[42:43], v[172:173], v[148:149]
	v_pk_fma_f32 v[150:151], s[42:43], v[172:173], v[150:151]
	v_pk_mul_f32 v[152:153], v[136:137], v[136:137]
	v_pk_fma_f32 v[152:153], v[138:139], v[138:139], v[152:153]
	v_pk_fma_f32 v[152:153], v[140:141], v[140:141], v[152:153]
	v_pk_fma_f32 v[152:153], v[142:143], v[142:143], v[152:153]
	v_pk_fma_f32 v[152:153], v[144:145], v[144:145], v[152:153]
	v_pk_fma_f32 v[152:153], v[146:147], v[146:147], v[152:153]
	v_pk_fma_f32 v[152:153], v[148:149], v[148:149], v[152:153]
	v_pk_fma_f32 v[152:153], v[150:151], v[150:151], v[152:153]
	v_add_f32_e32 v170, v152, v153
	s_nop 1
	v_add_f32_dpp v168, v170, v170 quad_perm:[1,0,3,2] row_mask:0xf bank_mask:0xf
	s_nop 1
	v_add_f32_dpp v168, v168, v168 quad_perm:[2,3,0,1] row_mask:0xf bank_mask:0xf
	s_nop 1
	v_add_f32_dpp v168, v168, v168 row_half_mirror row_mask:0xf bank_mask:0xf
	s_nop 1
	v_add_f32_dpp v168, v168, v168 row_mirror row_mask:0xf bank_mask:0xf
	s_nop 1
	v_add_f32_dpp v168, v168, v168 row_bcast:15 row_mask:0xa bank_mask:0xf
	s_nop 1
	v_add_f32_dpp v168, v168, v168 row_bcast:31 row_mask:0xc bank_mask:0xf
	s_nop 1
	v_readlane_b32 s42, v168, 63
	s_nop 3
	v_fma_f32 v174, s42, v178, v179
	v_rsq_f32_e32 v174, v174
	s_nop 0
	v_pk_mul_f32 v[136:137], v[136:137], v[174:175] op_sel_hi:[1,0]
	v_pk_mul_f32 v[138:139], v[138:139], v[174:175] op_sel_hi:[1,0]
	v_pk_mul_f32 v[140:141], v[140:141], v[174:175] op_sel_hi:[1,0]
	v_pk_mul_f32 v[142:143], v[142:143], v[174:175] op_sel_hi:[1,0]
	v_pk_mul_f32 v[144:145], v[144:145], v[174:175] op_sel_hi:[1,0]
	v_pk_mul_f32 v[146:147], v[146:147], v[174:175] op_sel_hi:[1,0]
	v_pk_mul_f32 v[148:149], v[148:149], v[174:175] op_sel_hi:[1,0]
	v_pk_mul_f32 v[150:151], v[150:151], v[174:175] op_sel_hi:[1,0]
	v_pk_fma_f32 v[136:137], v[136:137], v[0:1], v[16:17]
	v_pk_fma_f32 v[138:139], v[138:139], v[2:3], v[18:19]
	v_pk_fma_f32 v[140:141], v[140:141], v[4:5], v[20:21]
	v_pk_fma_f32 v[142:143], v[142:143], v[6:7], v[22:23]
	v_pk_fma_f32 v[144:145], v[144:145], v[8:9], v[24:25]
	v_pk_fma_f32 v[146:147], v[146:147], v[10:11], v[26:27]
	v_pk_fma_f32 v[148:149], v[148:149], v[12:13], v[28:29]
	v_pk_fma_f32 v[150:151], v[150:151], v[14:15], v[30:31]
	global_store_dwordx4 v176, v[136:139], s[8:9] offset:0
	global_store_dwordx4 v176, v[140:143], s[8:9] offset:1024
	global_store_dwordx4 v176, v[144:147], s[8:9] offset:2048
	global_store_dwordx4 v176, v[148:151], s[8:9] offset:3072
	s_add_u32 s8, s8, 0x1000
	s_addc_u32 s9, s9, 0
	s_add_u32 s12, s12, 0x800
	s_addc_u32 s13, s13, 0
	s_waitcnt vmcnt(8)
	v_lshlrev_b32_e32 v136, 16, v112
	v_and_b32_e32 v137, 0xffff0000, v112
	v_lshlrev_b32_e32 v138, 16, v113
	v_and_b32_e32 v139, 0xffff0000, v113
	v_lshlrev_b32_e32 v140, 16, v114
	v_and_b32_e32 v141, 0xffff0000, v114
	v_lshlrev_b32_e32 v142, 16, v115
	v_and_b32_e32 v143, 0xffff0000, v115
	v_lshlrev_b32_e32 v144, 16, v116
	v_and_b32_e32 v145, 0xffff0000, v116
	v_lshlrev_b32_e32 v146, 16, v117
	v_and_b32_e32 v147, 0xffff0000, v117
	v_lshlrev_b32_e32 v148, 16, v118
	v_and_b32_e32 v149, 0xffff0000, v118
	v_lshlrev_b32_e32 v150, 16, v119
	v_and_b32_e32 v151, 0xffff0000, v119
	v_pk_fma_f32 v[136:137], v[64:65], s[44:45], v[136:137]
	v_pk_fma_f32 v[138:139], v[66:67], s[44:45], v[138:139]
	v_pk_fma_f32 v[140:141], v[68:69], s[44:45], v[140:141]
	v_pk_fma_f32 v[142:143], v[70:71], s[44:45], v[142:143]
	v_pk_fma_f32 v[144:145], v[72:73], s[44:45], v[144:145]
	v_pk_fma_f32 v[146:147], v[74:75], s[44:45], v[146:147]
	v_pk_fma_f32 v[148:149], v[76:77], s[44:45], v[148:149]
	v_pk_fma_f32 v[150:151], v[78:79], s[44:45], v[150:151]
	v_pk_add_f32 v[152:153], v[136:137], v[138:139]
	v_pk_add_f32 v[152:153], v[152:153], v[140:141]
	v_pk_add_f32 v[152:153], v[152:153], v[142:143]
	v_pk_add_f32 v[152:153], v[152:153], v[144:145]
	v_pk_add_f32 v[152:153], v[152:153], v[146:147]
	v_pk_add_f32 v[152:153], v[152:153], v[148:149]
	v_pk_add_f32 v[152:153], v[152:153], v[150:151]
	v_add_f32_e32 v170, v152, v153
	s_nop 1
	v_add_f32_dpp v168, v170, v170 quad_perm:[1,0,3,2] row_mask:0xf bank_mask:0xf
	s_nop 1
	v_add_f32_dpp v168, v168, v168 quad_perm:[2,3,0,1] row_mask:0xf bank_mask:0xf
	s_nop 1
	v_add_f32_dpp v168, v168, v168 row_half_mirror row_mask:0xf bank_mask:0xf
	s_nop 1
	v_add_f32_dpp v168, v168, v168 row_mirror row_mask:0xf bank_mask:0xf
	s_nop 1
	v_add_f32_dpp v168, v168, v168 row_bcast:15 row_mask:0xa bank_mask:0xf
	s_nop 1
	v_add_f32_dpp v168, v168, v168 row_bcast:31 row_mask:0xc bank_mask:0xf
	s_nop 1
	v_readlane_b32 s42, v168, 63
	s_nop 3
	s_mov_b32 s43, s42
	v_pk_fma_f32 v[136:137], s[42:43], v[172:173], v[136:137]
	v_pk_fma_f32 v[138:139], s[42:43], v[172:173], v[138:139]
	v_pk_fma_f32 v[140:141], s[42:43], v[172:173], v[140:141]
	v_pk_fma_f32 v[142:143], s[42:43], v[172:173], v[142:143]
	v_pk_fma_f32 v[144:145], s[42:43], v[172:173], v[144:145]
	v_pk_fma_f32 v[146:147], s[42:43], v[172:173], v[146:147]
	v_pk_fma_f32 v[148:149], s[42:43], v[172:173], v[148:149]
	v_pk_fma_f32 v[150:151], s[42:43], v[172:173], v[150:151]
	v_pk_mul_f32 v[152:153], v[136:137], v[136:137]
	v_pk_fma_f32 v[152:153], v[138:139], v[138:139], v[152:153]
	v_pk_fma_f32 v[152:153], v[140:141], v[140:141], v[152:153]
	v_pk_fma_f32 v[152:153], v[142:143], v[142:143], v[152:153]
	v_pk_fma_f32 v[152:153], v[144:145], v[144:145], v[152:153]
	v_pk_fma_f32 v[152:153], v[146:147], v[146:147], v[152:153]
	v_pk_fma_f32 v[152:153], v[148:149], v[148:149], v[152:153]
	v_pk_fma_f32 v[152:153], v[150:151], v[150:151], v[152:153]
	v_add_f32_e32 v170, v152, v153
	s_nop 1
	v_add_f32_dpp v168, v170, v170 quad_perm:[1,0,3,2] row_mask:0xf bank_mask:0xf
	s_nop 1
	v_add_f32_dpp v168, v168, v168 quad_perm:[2,3,0,1] row_mask:0xf bank_mask:0xf
	s_nop 1
	v_add_f32_dpp v168, v168, v168 row_half_mirror row_mask:0xf bank_mask:0xf
	s_nop 1
	v_add_f32_dpp v168, v168, v168 row_mirror row_mask:0xf bank_mask:0xf
	s_nop 1
	v_add_f32_dpp v168, v168, v168 row_bcast:15 row_mask:0xa bank_mask:0xf
	s_nop 1
	v_add_f32_dpp v168, v168, v168 row_bcast:31 row_mask:0xc bank_mask:0xf
	s_nop 1
	v_readlane_b32 s42, v168, 63
	s_nop 3
	v_fma_f32 v174, s42, v178, v179
	v_rsq_f32_e32 v174, v174
	s_nop 0
	v_pk_mul_f32 v[136:137], v[136:137], v[174:175] op_sel_hi:[1,0]
	v_pk_mul_f32 v[138:139], v[138:139], v[174:175] op_sel_hi:[1,0]
	v_pk_mul_f32 v[140:141], v[140:141], v[174:175] op_sel_hi:[1,0]
	v_pk_mul_f32 v[142:143], v[142:143], v[174:175] op_sel_hi:[1,0]
	v_pk_mul_f32 v[144:145], v[144:145], v[174:175] op_sel_hi:[1,0]
	v_pk_mul_f32 v[146:147], v[146:147], v[174:175] op_sel_hi:[1,0]
	v_pk_mul_f32 v[148:149], v[148:149], v[174:175] op_sel_hi:[1,0]
	v_pk_mul_f32 v[150:151], v[150:151], v[174:175] op_sel_hi:[1,0]
	v_pk_fma_f32 v[136:137], v[136:137], v[0:1], v[16:17]
	v_pk_fma_f32 v[138:139], v[138:139], v[2:3], v[18:19]
	v_pk_fma_f32 v[140:141], v[140:141], v[4:5], v[20:21]
	v_pk_fma_f32 v[142:143], v[142:143], v[6:7], v[22:23]
	v_pk_fma_f32 v[144:145], v[144:145], v[8:9], v[24:25]
	v_pk_fma_f32 v[146:147], v[146:147], v[10:11], v[26:27]
	v_pk_fma_f32 v[148:149], v[148:149], v[12:13], v[28:29]
	v_pk_fma_f32 v[150:151], v[150:151], v[14:15], v[30:31]
	global_store_dwordx4 v176, v[136:139], s[8:9] offset:0
	global_store_dwordx4 v176, v[140:143], s[8:9] offset:1024
	global_store_dwordx4 v176, v[144:147], s[8:9] offset:2048
	global_store_dwordx4 v176, v[148:151], s[8:9] offset:3072
	s_add_u32 s8, s8, 0x1000
	s_addc_u32 s9, s9, 0
	s_add_u32 s12, s12, 0x800
	s_addc_u32 s13, s13, 0
